# scan: 34 per-head parameters resident in VGPRs; barrier: last leader releases every XCD line directly
# speedup vs baseline: 1.3974x; 1.0037x over previous
; DI float ex2(float x) { return __builtin_amdgcn_exp2f(x); }
; DI void scan_item(const Params& p, int L, int c, int item, char* smem, bool dry) {
;     ...
;   auto load_raw = [&](int tc) {
;     const int lr = b * 4096 + tc * 32 + tt;
;     const int s = c * 4096 + tc * 32 + tt;
;     const u16* cur = U + (size_t)lr * LDU_R;
;     const u16* prv = (s == 0) ? (BND + (size_t)4 * SHIFTW) : ((s == 4096 && c == 1) ? (BND + (size_t)b * SHIFTW) : (cur - LDU_R));
;     Rr_c = *(const uint4*)(cur + R_R + head * 64 + cs * 8);  Rr_p = *(const uint4*)(prv + R_R + head * 64 + cs * 8);
;     Rk_c = *(const uint4*)(cur + R_K + head * 64 + cs * 8);  Rk_p = *(const uint4*)(prv + R_K + head * 64 + cs * 8);
;     Rw_c = *(const uint4*)(cur + R_WD + cs * 8);             Rw_p = *(const uint4*)(prv + R_WD + cs * 8);
;     Ra_c = *(const uint4*)(cur + R_AD + cs * 8);             Ra_p = *(const uint4*)(prv + R_AD + cs * 8);
;     const int vo = R_V + head * 64 + 32 * half + c4 * 8;
;     Rv_c = *(const uint4*)(cur + vo);                        Rv_p = *(const uint4*)(prv + vo);
;   };
;   uint4 d_y = zero4, d_v = zero4; float d_sm = 0.f, d_sq = 0.f; int d_lr = -1;
;   auto flush_out = [&]() {
;     if (cs < 4 && !dry && d_lr >= 0) {
;       const size_t o = (size_t)d_lr * 1536 + head * 64 + 32 * half + cs * 8;
;       *(uint4*)(YR + o) = d_y;
;       *(uint4*)(BV + o) = d_v;
;       if (cs == 0) {
;         float* stp = ST + ((size_t)(d_lr * 24 + head) * 2 + half) * 2;
;         stp[0] = d_sm; stp[1] = d_sq;
;       }
;     }
;   };
;   float rm[8], km[8];
;   auto prep1 = [&](float* Vst) {
;     float cu[8], pv[8], t8[8];
;     unpack8(Rr_c, cu); unpack8(Rr_p, pv);
; #pragma unroll
;     for (int e = 0; e < 8; ++e) rm[e] = cu[e] + (pv[e] - cu[e]) * PRM[0 * 64 + cs * 8 + e];
;     unpack8(Rk_c, cu); unpack8(Rk_p, pv);
; #pragma unroll
;     for (int e = 0; e < 8; ++e) km[e] = cu[e] + (pv[e] - cu[e]) * PRM[1 * 64 + cs * 8 + e];
;     ...
;     for (int e = 0; e < 8; ++e) {
;       const int ch = cs * 8 + e;
;       const float sg = frcp(1.f + fexp(-(lw[e] + PRM[4 * 64 + ch])));
;       dec[e] = ex2(-0.8750340f * sg);
;       float a = frcp(1.f + fexp(-(la[e] + PRM[5 * 64 + ch])));
;       av[e] = a;
;       kk[e] = km[e] * PRM[6 * 64 + ch];
;       ssq += kk[e] * kk[e];
;       kp[e] = km[e] * (1.f + (a - 1.f) * PRM[7 * 64 + ch]);
;       bon += rm[e] * kp[e] * PRM[8 * 64 + ch];
;     }
.LBB0_151:
	s_or_saveexec_b64 s[6:7], s[6:7]
	v_mov_b64_e32 v[66:67], s[14:15]
	s_xor_b64 exec, exec, s[6:7]
	v_cmp_ne_u32_e32 vcc, 0, v41
	s_andn2_b64 s[12:13], s[12:13], exec
	s_and_b64 s[14:15], vcc, exec
	v_mov_b64_e32 v[66:67], s[96:97]
	s_or_b64 s[12:13], s[12:13], s[14:15]
	s_or_b64 exec, exec, s[6:7]
	v_add_u32_e32 v42, s23, v40
	v_mov_b64_e32 v[40:41], s[2:3]
	v_mad_i64_i32 v[68:69], s[6:7], v42, s66, v[40:41]
	s_and_saveexec_b64 s[6:7], s[12:13]
	s_movk_i32 s12, 0xc700
	s_mov_b32 s13, -1
	v_lshl_add_u64 v[66:67], v[68:69], 0, s[12:13]
	s_or_b64 exec, exec, s[6:7]
	v_lshlrev_b32_e32 v40, 16, v36
	v_and_b32_e32 v41, 0xffff0000, v36
	v_lshlrev_b32_e32 v44, 16, v32
	v_and_b32_e32 v45, 0xffff0000, v32
	v_lshlrev_b32_e32 v36, 16, v37
	v_and_b32_e32 v37, 0xffff0000, v37
	v_lshlrev_b32_e32 v32, 16, v33
	v_and_b32_e32 v33, 0xffff0000, v33
	v_pk_add_f32 v[44:45], v[44:45], v[40:41] neg_lo:[0,1] neg_hi:[0,1]
	v_lshlrev_b32_e32 v42, 16, v38
	v_and_b32_e32 v43, 0xffff0000, v38
	v_lshlrev_b32_e32 v46, 16, v34
	v_and_b32_e32 v47, 0xffff0000, v34
	v_pk_fma_f32 v[56:57], v[44:45], v[28:29], v[40:41]
	v_pk_add_f32 v[28:29], v[32:33], v[36:37] neg_lo:[0,1] neg_hi:[0,1]
	v_lshlrev_b32_e32 v38, 16, v39
	v_and_b32_e32 v39, 0xffff0000, v39
	v_lshlrev_b32_e32 v34, 16, v35
	v_and_b32_e32 v35, 0xffff0000, v35
	v_pk_fma_f32 v[58:59], v[28:29], v[30:31], v[36:37]
	v_pk_add_f32 v[28:29], v[46:47], v[42:43] neg_lo:[0,1] neg_hi:[0,1]
	v_lshlrev_b32_e32 v78, 16, v26
	v_pk_fma_f32 v[60:61], v[28:29], v[16:17], v[42:43]
	v_pk_add_f32 v[16:17], v[34:35], v[38:39] neg_lo:[0,1] neg_hi:[0,1]
	v_and_b32_e32 v79, 0xffff0000, v26
	v_pk_fma_f32 v[62:63], v[16:17], v[18:19], v[38:39]
	v_lshlrev_b32_e32 v16, 16, v24
	v_and_b32_e32 v17, 0xffff0000, v24
	v_lshlrev_b32_e32 v18, 16, v25
	v_and_b32_e32 v19, 0xffff0000, v25
	v_lshlrev_b32_e32 v24, 16, v20
	v_and_b32_e32 v25, 0xffff0000, v20
	v_lshlrev_b32_e32 v86, 16, v27
	v_and_b32_e32 v87, 0xffff0000, v27
	v_lshlrev_b32_e32 v20, 16, v21
	v_and_b32_e32 v21, 0xffff0000, v21
	v_lshlrev_b32_e32 v26, 16, v22
	v_and_b32_e32 v27, 0xffff0000, v22
	v_lshlrev_b32_e32 v80, 16, v23
	v_and_b32_e32 v81, 0xffff0000, v23
	v_pk_add_f32 v[22:23], v[24:25], v[16:17] neg_lo:[0,1] neg_hi:[0,1]
	s_movk_i32 s6, 0x2000
	v_pk_fma_f32 v[64:65], v[22:23], v[4:5], v[16:17]
	v_pk_add_f32 v[4:5], v[20:21], v[18:19] neg_lo:[0,1] neg_hi:[0,1]
	v_lshl_add_u64 v[16:17], v[68:69], 0, s[10:11]
	v_pk_fma_f32 v[4:5], v[4:5], v[6:7], v[18:19]
	v_lshl_add_u64 v[16:17], v[16:17], 0, v[198:199]
	v_lshl_add_u64 v[18:19], v[66:67], 0, s[10:11]
	v_lshl_add_u64 v[18:19], v[18:19], 0, v[198:199]
	global_load_dwordx4 v[48:51], v[16:17], off
	global_load_dwordx4 v[40:43], v[16:17], off offset:3072
	global_load_dwordx4 v[52:55], v[18:19], off
	global_load_dwordx4 v[44:47], v[18:19], off offset:3072
	v_lshl_add_u64 v[16:17], v[68:69], 0, v[198:199]
	v_add_co_u32_e32 v16, vcc, s6, v16
	v_lshl_add_u64 v[18:19], v[66:67], 0, v[198:199]
	s_nop 0
	v_addc_co_u32_e32 v17, vcc, 0, v17, vcc
	v_add_co_u32_e32 v18, vcc, s6, v18
	v_lshl_add_u64 v[20:21], v[66:67], 0, v[100:101]
	v_lshl_or_b32 v66, v71, 8, v136
	v_pk_add_f32 v[6:7], v[26:27], v[78:79] neg_lo:[0,1] neg_hi:[0,1]
	v_addc_co_u32_e32 v19, vcc, 0, v19, vcc
	global_load_dwordx4 v[32:35], v[16:17], off offset:1024
	global_load_dwordx4 v[24:27], v[16:17], off offset:1152
	global_load_dwordx4 v[36:39], v[18:19], off offset:1024
	global_load_dwordx4 v[28:31], v[18:19], off offset:1152
	v_lshl_add_u64 v[16:17], v[68:69], 0, v[100:101]
	v_add_u32_e32 v145, 0x20780, v66
	global_load_dwordx4 v[16:19], v[16:17], off
	v_pk_fma_f32 v[0:1], v[6:7], v[0:1], v[78:79]
	global_load_dwordx4 v[20:23], v[20:21], off
	s_waitcnt lgkmcnt(0)
	s_barrier
	ds_read_b128 v[66:69], v145
	ds_read_b128 v[74:77], v137 offset:1024
	v_pk_add_f32 v[6:7], v[80:81], v[86:87] neg_lo:[0,1] neg_hi:[0,1]
	ds_read_b128 v[78:81], v137 offset:1040
	ds_read_b128 v[82:85], v137 offset:2064
	v_pk_fma_f32 v[2:3], v[6:7], v[2:3], v[86:87]
	ds_read_b128 v[86:89], v145 offset:16
	ds_read_b128 v[90:93], v145 offset:8192
	ds_read_b128 v[102:105], v145 offset:8208
	s_waitcnt lgkmcnt(5)
	v_add_f32_e32 v66, v66, v74
	v_mul_f32_e32 v66, 0xbfb8aa3b, v66
	ds_read_b128 v[106:109], v137 offset:1280
	v_exp_f32_e32 v66, v66
	v_add_f32_e32 v7, v67, v75
	ds_read_b128 v[110:113], v137 offset:1296
	v_mul_f32_e32 v7, 0xbfb8aa3b, v7
	v_add_f32_e32 v6, 1.0, v66
	s_waitcnt lgkmcnt(1)
	v_add_f32_e32 v66, v90, v106
	v_mul_f32_e32 v66, 0xbfb8aa3b, v66
	v_exp_f32_e32 v66, v66
	v_add_f32_e32 v67, v91, v107
	v_mul_f32_e32 v67, 0xbfb8aa3b, v67
	v_exp_f32_e32 v67, v67
	v_add_f32_e32 v66, 1.0, v66
	v_rcp_f32_e32 v90, v66
	v_add_f32_e32 v66, v68, v76
	v_mul_f32_e32 v66, 0xbfb8aa3b, v66
	v_add_f32_e32 v67, 1.0, v67
	v_exp_f32_e32 v66, v66
	v_rcp_f32_e32 v91, v67
	v_add_f32_e32 v67, v69, v77
	v_mul_f32_e32 v67, 0xbfb8aa3b, v67
	v_exp_f32_e32 v67, v67
	v_add_f32_e32 v66, 1.0, v66
	v_add_f32_e32 v68, v92, v108
	v_rcp_f32_e32 v66, v66
	v_mul_f32_e32 v68, 0xbfb8aa3b, v68
	v_exp_f32_e32 v68, v68
	v_add_f32_e32 v67, 1.0, v67
	v_rcp_f32_e32 v67, v67
	v_mul_f32_e32 v66, 0xbf60023a, v66
	v_exp_f32_e32 v92, v66
	v_add_f32_e32 v66, 1.0, v68
	v_rcp_f32_e32 v94, v66
	v_mul_f32_e32 v66, 0xbf60023a, v67
	v_add_f32_e32 v67, v86, v78
	v_mul_f32_e32 v67, 0xbfb8aa3b, v67
	v_exp_f32_e32 v67, v67
	v_add_f32_e32 v68, v93, v109
	v_mul_f32_e32 v68, 0xbfb8aa3b, v68
	v_exp_f32_e32 v68, v68
	v_add_f32_e32 v67, 1.0, v67
	v_rcp_f32_e32 v67, v67
	v_exp_f32_e32 v93, v66
	v_add_f32_e32 v66, 1.0, v68
	v_rcp_f32_e32 v95, v66
	v_mul_f32_e32 v66, 0xbf60023a, v67
	v_add_f32_e32 v67, v87, v79
	v_mul_f32_e32 v67, 0xbfb8aa3b, v67
	v_exp_f32_e32 v67, v67
	s_waitcnt lgkmcnt(0)
; DI float ex2(float x) { return __builtin_amdgcn_exp2f(x); }
; DI float fexp(float x) { return __builtin_amdgcn_exp2f(x * 1.4426950408889634f); }
; DI float frcp(float x) { return __builtin_amdgcn_rcpf(x); }
; DI float red8(float x) { x += dppf(x, 0); x += dppf(x, 1); x += dppf(x, 2); return x; }
; DI void scan_item(const Params& p, int L, int c, int item, char* smem, bool dry) {
;     ...
;     float dec[8], kk[8], av[8], kp[8];
;     float ssq = 0.f, bon = 0.f;
; #pragma unroll
;     for (int e = 0; e < 8; ++e) {
;       const int ch = cs * 8 + e;
;       const float sg = frcp(1.f + fexp(-(lw[e] + PRM[4 * 64 + ch])));
;       dec[e] = ex2(-0.8750340f * sg);
;       float a = frcp(1.f + fexp(-(la[e] + PRM[5 * 64 + ch])));
;       av[e] = a;
;       kk[e] = km[e] * PRM[6 * 64 + ch];
;       ssq += kk[e] * kk[e];
;       kp[e] = km[e] * (1.f + (a - 1.f) * PRM[7 * 64 + ch]);
;       bon += rm[e] * kp[e] * PRM[8 * 64 + ch];
;     }
;     ssq = red8(ssq); bon = red8(bon);
;     const float inv = fminf(__builtin_amdgcn_rsqf(ssq), 1e12f);
;     float nk[8], bb[8];
; #pragma unroll
;     for (int e = 0; e < 8; ++e) { float kn = kk[e] * inv; nk[e] = -kn; bb[e] = kn * av[e]; }
;     float* pa = PA + tt * 320 + cs * 8;
;     *(float4*)(pa) = make_float4(dec[0], dec[1], dec[2], dec[3]); *(float4*)(pa + 4) = make_float4(dec[4], dec[5], dec[6], dec[7]);
;     *(float4*)(pa + 64) = make_float4(nk[0], nk[1], nk[2], nk[3]); *(float4*)(pa + 68) = make_float4(nk[4], nk[5], nk[6], nk[7]);
;     *(float4*)(pa + 128) = make_float4(bb[0], bb[1], bb[2], bb[3]); *(float4*)(pa + 132) = make_float4(bb[4], bb[5], bb[6], bb[7]);
;     *(float4*)(pa + 192) = make_float4(kp[0], kp[1], kp[2], kp[3]); *(float4*)(pa + 196) = make_float4(kp[4], kp[5], kp[6], kp[7]);
;     *(float4*)(pa + 256) = make_float4(rm[0], rm[1], rm[2], rm[3]); *(float4*)(pa + 260) = make_float4(rm[4], rm[5], rm[6], rm[7]);
;     BON[tt] = bon;
	v_add_f32_e32 v68, v102, v110
	v_mul_f32_e32 v68, 0xbfb8aa3b, v68
	v_exp_f32_e32 v68, v68
	v_add_f32_e32 v67, 1.0, v67
	v_rcp_f32_e32 v67, v67
	v_exp_f32_e32 v78, v66
	v_add_f32_e32 v66, 1.0, v68
	v_rcp_f32_e32 v86, v66
	v_mul_f32_e32 v66, 0xbf60023a, v67
	v_add_f32_e32 v67, v88, v80
	v_mul_f32_e32 v67, 0xbfb8aa3b, v67
	v_exp_f32_e32 v67, v67
	v_add_f32_e32 v68, v103, v111
	v_mul_f32_e32 v68, 0xbfb8aa3b, v68
	v_exp_f32_e32 v68, v68
	v_add_f32_e32 v67, 1.0, v67
	v_rcp_f32_e32 v67, v67
	v_exp_f32_e32 v79, v66
	v_add_f32_e32 v66, 1.0, v68
	v_rcp_f32_e32 v87, v66
	v_mul_f32_e32 v66, 0xbf60023a, v67
	v_add_f32_e32 v67, v104, v112
	v_mul_f32_e32 v67, 0xbfb8aa3b, v67
	v_add_f32_e32 v68, v89, v81
	v_exp_f32_e32 v67, v67
	v_mul_f32_e32 v68, 0xbfb8aa3b, v68
	v_exp_f32_e32 v68, v68
	v_exp_f32_e32 v80, v66
	v_add_f32_e32 v66, 1.0, v67
	v_rcp_f32_e32 v88, v66
	v_add_f32_e32 v66, 1.0, v68
	v_rcp_f32_e32 v73, v66
	v_add_f32_e32 v66, v105, v113
	v_mul_f32_e32 v66, 0xbfb8aa3b, v66
	v_exp_f32_e32 v74, v66
	ds_read_b128 v[66:69], v137 offset:1536
	v_mul_f32_e32 v73, 0xbf60023a, v73
	v_exp_f32_e32 v81, v73
	v_add_f32_e32 v73, 1.0, v74
	ds_read_b128 v[74:77], v137 offset:1552
	s_waitcnt lgkmcnt(1)
	v_pk_mul_f32 v[66:67], v[64:65], v[66:67]
	v_pk_mul_f32 v[68:69], v[4:5], v[68:69]
	v_pk_mul_f32 v[102:103], v[66:67], v[66:67]
	v_pk_mul_f32 v[104:105], v[68:69], v[68:69]
	v_add_f32_e32 v89, v102, v103
	s_waitcnt lgkmcnt(0)
	v_pk_mul_f32 v[74:75], v[0:1], v[74:75]
	v_add_f32_e32 v89, v89, v104
	v_pk_mul_f32 v[106:107], v[74:75], v[74:75]
	v_add_f32_e32 v89, v89, v105
	v_pk_mul_f32 v[76:77], v[2:3], v[76:77]
	v_add_f32_e32 v89, v89, v106
	v_pk_mul_f32 v[108:109], v[76:77], v[76:77]
	v_add_f32_e32 v89, v89, v107
	v_add_f32_e32 v89, v89, v108
	v_add_f32_e32 v89, v89, v109
	v_exp_f32_e32 v7, v7
	v_rcp_f32_e32 v6, v6
	v_add_f32_dpp v89, v89, v89 quad_perm:[1,0,3,2] row_mask:0xf bank_mask:0xf bound_ctrl:1
	s_movk_i32 s6, 0x500
	v_add_f32_e32 v7, 1.0, v7
	v_add_f32_dpp v89, v89, v89 quad_perm:[2,3,0,1] row_mask:0xf bank_mask:0xf bound_ctrl:1
	v_rcp_f32_e32 v7, v7
	v_mul_f32_e32 v6, 0xbf60023a, v6
	v_add_f32_dpp v89, v89, v89 row_half_mirror row_mask:0xf bank_mask:0xf bound_ctrl:1
	v_rsq_f32_e32 v102, v89
	v_mul_f32_e32 v7, 0xbf60023a, v7
	v_exp_f32_e32 v6, v6
	v_exp_f32_e32 v7, v7
	v_min_f32_e32 v102, 0x5368d4a5, v102
	v_pk_mul_f32 v[104:105], v[66:67], v[102:103] op_sel_hi:[1,0] neg_lo:[0,1] neg_hi:[0,1]
	v_pk_mul_f32 v[106:107], v[68:69], v[102:103] op_sel_hi:[1,0] neg_lo:[0,1] neg_hi:[0,1]
	ds_read_b128 v[66:69], v137 offset:2048
	ds_read_b64 v[108:109], v137 offset:1792
	v_rcp_f32_e32 v89, v73
	v_mul_lo_u32 v73, v71, s6
	v_pk_mul_f32 v[74:75], v[74:75], v[102:103] op_sel_hi:[1,0] neg_lo:[0,1] neg_hi:[0,1]
	v_pk_mul_f32 v[76:77], v[76:77], v[102:103] op_sel_hi:[1,0] neg_lo:[0,1] neg_hi:[0,1]
	v_pk_mul_f32 v[102:103], v[90:91], v[104:105] neg_lo:[0,1] neg_hi:[0,1]
	v_pk_add_f32 v[90:91], v[90:91], -1.0 op_sel_hi:[1,0]
	v_or_b32_e32 v146, v136, v73
	s_waitcnt lgkmcnt(0)
	v_pk_fma_f32 v[90:91], v[108:109], v[90:91], 1.0 op_sel_hi:[1,1,0]
	v_pk_mul_f32 v[110:111], v[94:95], v[106:107] neg_lo:[0,1] neg_hi:[0,1]
	v_pk_mul_f32 v[64:65], v[64:65], v[90:91]
	ds_write_b64 v146, v[6:7]
	ds_write_b64 v146, v[104:105] offset:256
	ds_write_b64 v146, v[102:103] offset:512
	ds_write_b64 v146, v[64:65] offset:768
	ds_read_b64 v[6:7], v137 offset:1800
	v_pk_mul_f32 v[90:91], v[56:57], v[64:65]
	v_pk_add_f32 v[64:65], v[94:95], -1.0 op_sel_hi:[1,0]
	v_fma_f32 v66, v66, v90, 0
	v_fmac_f32_e32 v66, v67, v91
	s_waitcnt lgkmcnt(0)
	v_pk_fma_f32 v[6:7], v[6:7], v[64:65], 1.0 op_sel_hi:[1,1,0]
	v_pk_mul_f32 v[112:113], v[86:87], v[74:75] neg_lo:[0,1] neg_hi:[0,1]
	v_pk_mul_f32 v[4:5], v[4:5], v[6:7]
	ds_write_b64 v146, v[92:93] offset:8
	ds_write_b64 v146, v[106:107] offset:264
	ds_write_b64 v146, v[110:111] offset:520
	ds_write_b64 v146, v[4:5] offset:776
	ds_read_b64 v[6:7], v137 offset:1808
	v_pk_mul_f32 v[4:5], v[58:59], v[4:5]
	v_readlane_b32 s6, v255, 18
	v_fmac_f32_e32 v66, v68, v4
	v_fmac_f32_e32 v66, v69, v5
	v_pk_add_f32 v[4:5], v[86:87], -1.0 op_sel_hi:[1,0]
	v_cmp_lt_u32_e32 vcc, 3, v70
	s_waitcnt lgkmcnt(0)
	v_pk_fma_f32 v[4:5], v[6:7], v[4:5], 1.0 op_sel_hi:[1,1,0]
	v_readlane_b32 s7, v255, 19
	v_pk_mul_f32 v[0:1], v[0:1], v[4:5]
	ds_write_b64 v146, v[78:79] offset:16
	ds_write_b64 v146, v[74:75] offset:272
	ds_write_b64 v146, v[112:113] offset:528
	ds_write_b64 v146, v[0:1] offset:784
	ds_read_b64 v[4:5], v137 offset:1816
	v_pk_mul_f32 v[0:1], v[60:61], v[0:1]
	s_or_b64 s[16:17], s[6:7], vcc
	v_fmac_f32_e32 v66, v82, v0
	v_fmac_f32_e32 v66, v83, v1
	v_pk_add_f32 v[0:1], v[88:89], -1.0 op_sel_hi:[1,0]
	s_add_u32 s12, s40, s22
	s_waitcnt lgkmcnt(0)
; DI float red8(float x) { x += dppf(x, 0); x += dppf(x, 1); x += dppf(x, 2); return x; }
; DI void scan_item(const Params& p, int L, int c, int item, char* smem, bool dry) {
;     ...
;     ssq = red8(ssq); bon = red8(bon);
;     const float inv = fminf(__builtin_amdgcn_rsqf(ssq), 1e12f);
;     float nk[8], bb[8];
; #pragma unroll
;     for (int e = 0; e < 8; ++e) { float kn = kk[e] * inv; nk[e] = -kn; bb[e] = kn * av[e]; }
;     float* pa = PA + tt * 320 + cs * 8;
;     *(float4*)(pa) = make_float4(dec[0], dec[1], dec[2], dec[3]); *(float4*)(pa + 4) = make_float4(dec[4], dec[5], dec[6], dec[7]);
;     *(float4*)(pa + 64) = make_float4(nk[0], nk[1], nk[2], nk[3]); *(float4*)(pa + 68) = make_float4(nk[4], nk[5], nk[6], nk[7]);
;     *(float4*)(pa + 128) = make_float4(bb[0], bb[1], bb[2], bb[3]); *(float4*)(pa + 132) = make_float4(bb[4], bb[5], bb[6], bb[7]);
;     *(float4*)(pa + 192) = make_float4(kp[0], kp[1], kp[2], kp[3]); *(float4*)(pa + 196) = make_float4(kp[4], kp[5], kp[6], kp[7]);
;     *(float4*)(pa + 256) = make_float4(rm[0], rm[1], rm[2], rm[3]); *(float4*)(pa + 260) = make_float4(rm[4], rm[5], rm[6], rm[7]);
;     BON[tt] = bon;
;     ...
;   load_raw(0);
;   prep1(Vstb);
;   __syncthreads();
;   prep3();
;   load_raw(1);
;   __syncthreads();
;   prep4(PAb, BONb);
;   __syncthreads();
;   int v3 = 0;
	v_pk_fma_f32 v[0:1], v[4:5], v[0:1], 1.0 op_sel_hi:[1,1,0]
	s_addc_u32 s13, s41, s20
	v_pk_mul_f32 v[0:1], v[2:3], v[0:1]
	s_lshl_b32 s20, s18, 3
	v_pk_mul_f32 v[2:3], v[62:63], v[0:1]
	v_readlane_b32 s14, v252, 56
	v_fmac_f32_e32 v66, v84, v2
	v_fmac_f32_e32 v66, v85, v3
	v_pk_mul_f32 v[114:115], v[88:89], v[76:77] neg_lo:[0,1] neg_hi:[0,1]
	ds_write_b64 v146, v[80:81] offset:24
	ds_write_b64 v146, v[76:77] offset:280
	ds_write_b64 v146, v[114:115] offset:536
	v_add_f32_dpp v2, v66, v66 quad_perm:[1,0,3,2] row_mask:0xf bank_mask:0xf bound_ctrl:1
	ds_write_b64 v146, v[0:1] offset:792
	ds_write_b128 v146, v[56:59] offset:1024
	ds_write_b128 v146, v[60:63] offset:1040
	v_add_f32_dpp v2, v2, v2 quad_perm:[2,3,0,1] row_mask:0xf bank_mask:0xf bound_ctrl:1
	v_mov_b32_e32 v0, 0x19a00
	v_readlane_b32 s15, v252, 57
	s_add_u32 s14, s14, s20
	v_mov_b32_e32 v104, 0
	v_add_f32_dpp v2, v2, v2 row_half_mirror row_mask:0xf bank_mask:0xf bound_ctrl:1
	v_lshl_add_u32 v147, v71, 2, v0
	s_addc_u32 s15, s15, 0
	s_or_b32 s0, s0, s19
	v_readlane_b32 s18, v255, 14
	s_mov_b32 s30, 1
	s_mov_b32 s29, 0
	ds_write_b32 v147, v2
	v_cmp_eq_u32_e64 s[6:7], 0, v70
	v_lshl_add_u64 v[102:103], s[0:1], 0, v[98:99]
	v_add_u32_e32 v99, s18, v71
	v_mov_b32_e32 v152, -1
	s_xor_b64 s[16:17], s[16:17], -1
	v_lshlrev_b32_e32 v148, 2, v72
	s_mov_b32 s31, 0
	v_mov_b32_e32 v105, v104
	v_mov_b32_e32 v4, v104
	v_mov_b32_e32 v5, v104
	v_mov_b32_e32 v6, v104
	v_mov_b32_e32 v7, v104
	v_mov_b32_e32 v0, v104
	v_mov_b32_e32 v1, v104
	v_mov_b32_e32 v2, v104
	v_mov_b32_e32 v3, v104
	ds_read_b128 v[168:171], v137 offset:512
	ds_read_b128 v[172:175], v137 offset:528
	ds_read_b128 v[190:193], v137 offset:256
	ds_read_b128 v[200:203], v137 offset:272
	ds_read_b128 v[240:243], v137
	ds_read_b64 v[176:177], v137 offset:16
	ds_read_b64 v[204:205], v137 offset:768
	ds_read_b64 v[234:235], v137 offset:784
	ds_read_b64 v[236:237], v137 offset:24
	s_waitcnt lgkmcnt(0)
	v_accvgpr_write_b32 a42, v236
	v_accvgpr_write_b32 a43, v237
	ds_read_b64 v[236:237], v137 offset:776
	s_waitcnt lgkmcnt(0)
	v_accvgpr_write_b32 a44, v236
	v_accvgpr_write_b32 a45, v237
	ds_read_b64 v[236:237], v137 offset:792
	s_waitcnt lgkmcnt(0)
	v_accvgpr_write_b32 a46, v236
	v_accvgpr_write_b32 a47, v237
	ds_read_b128 v[244:247], v143 offset:2304
	ds_read_b128 v[248:251], v143 offset:2320
	ds_read_b128 v[236:239], v137 offset:1024
	s_waitcnt lgkmcnt(0)
	v_accvgpr_write_b32 a56, v236
	v_accvgpr_write_b32 a57, v237
	v_accvgpr_write_b32 a58, v238
	v_accvgpr_write_b32 a59, v239
	ds_read_b128 v[236:239], v137 offset:1040
	s_waitcnt lgkmcnt(0)
	v_accvgpr_write_b32 a60, v236
	v_accvgpr_write_b32 a61, v237
	v_accvgpr_write_b32 a62, v238
	v_accvgpr_write_b32 a63, v239
	ds_read_b128 v[236:239], v137 offset:1536
	s_waitcnt lgkmcnt(0)
	v_accvgpr_write_b32 a64, v236
	v_accvgpr_write_b32 a65, v237
	v_accvgpr_write_b32 a66, v238
	v_accvgpr_write_b32 a67, v239
	ds_read_b128 v[236:239], v137 offset:1280
	s_waitcnt lgkmcnt(0)
	v_accvgpr_write_b32 a68, v236
	v_accvgpr_write_b32 a69, v237
	v_accvgpr_write_b32 a70, v238
	v_accvgpr_write_b32 a71, v239
	ds_read_b128 v[236:239], v137 offset:1552
	s_waitcnt lgkmcnt(0)
	v_accvgpr_write_b32 a72, v236
	v_accvgpr_write_b32 a73, v237
	v_accvgpr_write_b32 a74, v238
	v_accvgpr_write_b32 a75, v239
	ds_read_b128 v[236:239], v137 offset:1296
	s_waitcnt lgkmcnt(0)
	v_accvgpr_write_b32 a76, v236
	v_accvgpr_write_b32 a77, v237
	v_accvgpr_write_b32 a78, v238
	v_accvgpr_write_b32 a79, v239
	ds_read_b128 v[236:239], v137 offset:1792
	s_waitcnt lgkmcnt(0)
	v_accvgpr_write_b32 a80, v236
	v_accvgpr_write_b32 a81, v237
	v_accvgpr_write_b32 a82, v238
	v_accvgpr_write_b32 a83, v239
	ds_read_b128 v[236:239], v137 offset:2048
	s_waitcnt lgkmcnt(0)
	v_accvgpr_write_b32 a84, v236
	v_accvgpr_write_b32 a85, v237
	v_accvgpr_write_b32 a86, v238
	v_accvgpr_write_b32 a87, v239
	ds_read_b128 v[236:239], v137 offset:1808
	s_waitcnt lgkmcnt(0)
	v_accvgpr_write_b32 a88, v236
	v_accvgpr_write_b32 a89, v237
	v_accvgpr_write_b32 a90, v238
	v_accvgpr_write_b32 a91, v239
	ds_read_b128 v[236:239], v137 offset:2064
	s_waitcnt lgkmcnt(0)
	v_accvgpr_write_b32 a92, v236
	v_accvgpr_write_b32 a93, v237
	v_accvgpr_write_b32 a94, v238
	v_accvgpr_write_b32 a95, v239
	s_waitcnt lgkmcnt(0)
	s_barrier
; DI float ex2(float x) { return __builtin_amdgcn_exp2f(x); }
; DI float frcp(float x) { return __builtin_amdgcn_rcpf(x); }
; DI uint4 pack8(const float* f) { uint4 v; v.x = pack2(f[0], f[1]); v.y = pack2(f[2], f[3]); v.z = pack2(f[4], f[5]); v.w = pack2(f[6], f[7]); return v; }
; DI void scan_item(const Params& p, int L, int c, int item, char* smem, bool dry) {
;     ...
;   auto prep1 = [&](float* Vst) {
;     float cu[8], pv[8], t8[8];
;     unpack8(Rr_c, cu); unpack8(Rr_p, pv);
; #pragma unroll
;     for (int e = 0; e < 8; ++e) rm[e] = cu[e] + (pv[e] - cu[e]) * PRM[0 * 64 + cs * 8 + e];
;     unpack8(Rk_c, cu); unpack8(Rk_p, pv);
; #pragma unroll
;     for (int e = 0; e < 8; ++e) km[e] = cu[e] + (pv[e] - cu[e]) * PRM[1 * 64 + cs * 8 + e];
;     unpack8(Rw_c, cu); unpack8(Rw_p, pv);
; #pragma unroll
;     for (int e = 0; e < 8; ++e) {
;       float xw = cu[e] + (pv[e] - cu[e]) * PRM[2 * 64 + cs * 8 + e];
;       float ee = ex2(xw * 2.8853900817779268f);
;       t8[e] = 1.f - 2.f * frcp(ee + 1.f);
;     }
;     *(uint4*)(A1 + (0 * 32 + tt) * 72 + cs * 8) = pack8(t8);
;     unpack8(Ra_c, cu); unpack8(Ra_p, pv);
; #pragma unroll
;     for (int e = 0; e < 8; ++e) t8[e] = cu[e] + (pv[e] - cu[e]) * PRM[3 * 64 + cs * 8 + e];
;     ...
;   auto step_load = [&](const float* PA, const float* Vst, int t) {
;     const float* pa = PA + t * 320 + ks * 8;
;     d0 = *(const float4*)(pa); d1 = *(const float4*)(pa + 4);
;     n0 = *(const float4*)(pa + 64); n1 = *(const float4*)(pa + 68);
;     b0 = *(const float4*)(pa + 128); b1 = *(const float4*)(pa + 132);
;     k0 = *(const float4*)(pa + 192); k1 = *(const float4*)(pa + 196);
;     r0 = *(const float4*)(pa + 256); r1 = *(const float4*)(pa + 260);
;     vv = Vst[t * 32 + row32];
;   };
.LBB0_156:
	s_add_i32 s18, s30, -1
	s_add_i32 s19, s31, 1
	s_cmp_lg_u32 s31, 2
	s_cselect_b32 s34, s19, 0
	s_and_b32 s19, s18, 1
	s_mul_i32 s22, s19, 0xa000
	v_or_b32_e32 v149, s22, v136
	ds_read_b128 v[64:67], v149
	ds_read_b128 v[76:79], v149 offset:16
	ds_read_b128 v[92:95], v149 offset:256
	ds_read_b128 v[88:91], v149 offset:272
	ds_read_b128 v[68:71], v149 offset:512
	ds_read_b128 v[80:83], v149 offset:528
	ds_read_b128 v[72:75], v149 offset:768
	ds_read_b128 v[84:87], v149 offset:784
	ds_read_b128 v[60:63], v149 offset:1024
	ds_read_b128 v[56:59], v149 offset:1040
	s_waitcnt vmcnt(9)
	v_lshlrev_b32_e32 v112, 16, v48
	v_and_b32_e32 v113, 0xffff0000, v48
	v_lshlrev_b32_e32 v110, 16, v49
	v_and_b32_e32 v111, 0xffff0000, v49
	v_lshlrev_b32_e32 v108, 16, v50
	v_and_b32_e32 v109, 0xffff0000, v50
	v_lshlrev_b32_e32 v48, 16, v51
	v_and_b32_e32 v49, 0xffff0000, v51
	s_waitcnt vmcnt(7)
	v_lshlrev_b32_e32 v116, 16, v52
	v_and_b32_e32 v117, 0xffff0000, v52
	v_lshlrev_b32_e32 v114, 16, v53
	v_and_b32_e32 v115, 0xffff0000, v53
	v_lshlrev_b32_e32 v52, 16, v54
	v_and_b32_e32 v53, 0xffff0000, v54
	v_lshlrev_b32_e32 v50, 16, v55
	v_and_b32_e32 v51, 0xffff0000, v55
	v_lshlrev_b32_e32 v120, 16, v40
	v_and_b32_e32 v121, 0xffff0000, v40
	v_lshlrev_b32_e32 v118, 16, v41
	v_and_b32_e32 v119, 0xffff0000, v41
	v_lshlrev_b32_e32 v54, 16, v42
	v_and_b32_e32 v55, 0xffff0000, v42
	v_lshlrev_b32_e32 v40, 16, v43
	v_and_b32_e32 v41, 0xffff0000, v43
	s_waitcnt vmcnt(6)
	v_lshlrev_b32_e32 v124, 16, v44
	v_and_b32_e32 v125, 0xffff0000, v44
	v_lshlrev_b32_e32 v122, 16, v45
	v_and_b32_e32 v123, 0xffff0000, v45
	v_lshlrev_b32_e32 v44, 16, v46
	v_and_b32_e32 v45, 0xffff0000, v46
	v_lshlrev_b32_e32 v42, 16, v47
	v_and_b32_e32 v43, 0xffff0000, v47
	s_waitcnt vmcnt(5)
	v_lshlrev_b32_e32 v46, 16, v32
	s_waitcnt vmcnt(3)
	v_lshlrev_b32_e32 v47, 16, v36
	v_and_b32_e32 v32, 0xffff0000, v32
	v_and_b32_e32 v36, 0xffff0000, v36
	v_sub_f32_e32 v36, v36, v32
	v_fmac_f32_e32 v32, v36, v169
	v_mul_f32_e32 v32, 0x4038aa3b, v32
	v_exp_f32_e32 v32, v32
	v_sub_f32_e32 v47, v47, v46
	v_fmac_f32_e32 v46, v47, v168
	v_lshlrev_b32_e32 v36, 16, v37
	v_add_f32_e32 v32, 1.0, v32
	v_rcp_f32_e32 v47, v32
	v_lshlrev_b32_e32 v32, 16, v33
	v_sub_f32_e32 v36, v36, v32
	v_fmac_f32_e32 v32, v36, v170
	v_and_b32_e32 v33, 0xffff0000, v33
	v_and_b32_e32 v36, 0xffff0000, v37
	v_sub_f32_e32 v36, v36, v33
	v_fmac_f32_e32 v33, v36, v171
	v_lshlrev_b32_e32 v36, 16, v34
	v_lshlrev_b32_e32 v37, 16, v38
	v_sub_f32_e32 v37, v37, v36
	v_and_b32_e32 v34, 0xffff0000, v34
	v_fmac_f32_e32 v36, v37, v172
	v_and_b32_e32 v37, 0xffff0000, v38
	v_sub_f32_e32 v37, v37, v34
	v_fmac_f32_e32 v34, v37, v173
	v_mul_f32_e32 v34, 0x4038aa3b, v34
	v_exp_f32_e32 v34, v34
	v_lshlrev_b32_e32 v38, 16, v39
	v_mul_f32_e32 v32, 0x4038aa3b, v32
	v_mul_f32_e32 v33, 0x4038aa3b, v33
	v_add_f32_e32 v34, 1.0, v34
	v_rcp_f32_e32 v37, v34
	v_lshlrev_b32_e32 v34, 16, v35
	v_sub_f32_e32 v38, v38, v34
	v_fmac_f32_e32 v34, v38, v174
	v_and_b32_e32 v35, 0xffff0000, v35
	v_and_b32_e32 v38, 0xffff0000, v39
	v_sub_f32_e32 v38, v38, v35
	v_fmac_f32_e32 v35, v38, v175
	v_mul_f32_e32 v36, 0x4038aa3b, v36
	v_mul_f32_e32 v34, 0x4038aa3b, v34
	v_mul_f32_e32 v35, 0x4038aa3b, v35
	v_exp_f32_e32 v32, v32
	v_exp_f32_e32 v33, v33
	v_exp_f32_e32 v36, v36
	v_exp_f32_e32 v34, v34
	v_exp_f32_e32 v35, v35
	s_waitcnt vmcnt(1)
	v_lshlrev_b32_e32 v130, 16, v16
	v_and_b32_e32 v131, 0xffff0000, v16
	v_lshlrev_b32_e32 v126, 16, v17
	v_and_b32_e32 v127, 0xffff0000, v17
	s_waitcnt lgkmcnt(7)
	v_pk_mul_f32 v[16:17], v[8:9], v[92:93]
	v_add_f32_e32 v32, 1.0, v32
	v_add_f32_e32 v33, 1.0, v33
	v_add_f32_e32 v36, 1.0, v36
	v_add_f32_e32 v34, 1.0, v34
	v_add_f32_e32 v35, 1.0, v35
	v_pk_fma_f32 v[16:17], v[10:11], v[94:95], v[16:17]
	v_rcp_f32_e32 v32, v32
	v_rcp_f32_e32 v33, v33
	v_rcp_f32_e32 v36, v36
	v_rcp_f32_e32 v34, v34
	v_rcp_f32_e32 v35, v35
	s_waitcnt lgkmcnt(6)
	v_pk_fma_f32 v[16:17], v[12:13], v[88:89], v[16:17]
	v_pk_fma_f32 v[32:33], v[32:33], 2.0, 1.0 op_sel_hi:[1,0,0] neg_lo:[1,0,0] neg_hi:[1,0,0]
	v_pk_fma_f32 v[16:17], v[14:15], v[90:91], v[16:17]
	v_pk_fma_f32 v[36:37], v[36:37], 2.0, 1.0 op_sel_hi:[1,0,0] neg_lo:[1,0,0] neg_hi:[1,0,0]
	v_add_f32_e32 v16, v16, v17
	v_pk_fma_f32 v[34:35], v[34:35], 2.0, 1.0 op_sel_hi:[1,0,0] neg_lo:[1,0,0] neg_hi:[1,0,0]
	v_cvt_pk_bf16_f32 v129, v32, v33
	v_add_f32_dpp v16, v16, v16 quad_perm:[1,0,3,2] row_mask:0xf bank_mask:0xf bound_ctrl:1
	v_cvt_pk_bf16_f32 v154, v36, v37
	v_cvt_pk_bf16_f32 v155, v34, v35
	v_add_f32_dpp v16, v16, v16 quad_perm:[2,3,0,1] row_mask:0xf bank_mask:0xf bound_ctrl:1
	v_lshlrev_b32_e32 v36, 16, v18
	v_and_b32_e32 v37, 0xffff0000, v18
	v_lshlrev_b32_e32 v34, 16, v19
	v_and_b32_e32 v35, 0xffff0000, v19
	v_add_f32_dpp v32, v16, v16 row_half_mirror row_mask:0xf bank_mask:0xf bound_ctrl:1
	v_mul_f32_e32 v46, 0x4038aa3b, v46
	v_exp_f32_e32 v46, v46
	s_waitcnt vmcnt(0)
; DI float ex2(float x) { return __builtin_amdgcn_exp2f(x); }
; DI float frcp(float x) { return __builtin_amdgcn_rcpf(x); }
; DI uint4 pack8(const float* f) { uint4 v; v.x = pack2(f[0], f[1]); v.y = pack2(f[2], f[3]); v.z = pack2(f[4], f[5]); v.w = pack2(f[6], f[7]); return v; }
; DI void scan_item(const Params& p, int L, int c, int item, char* smem, bool dry) {
;     ...
;   auto prep1 = [&](float* Vst) {
;     float cu[8], pv[8], t8[8];
;     unpack8(Rr_c, cu); unpack8(Rr_p, pv);
; #pragma unroll
;     for (int e = 0; e < 8; ++e) rm[e] = cu[e] + (pv[e] - cu[e]) * PRM[0 * 64 + cs * 8 + e];
;     unpack8(Rk_c, cu); unpack8(Rk_p, pv);
; #pragma unroll
;     for (int e = 0; e < 8; ++e) km[e] = cu[e] + (pv[e] - cu[e]) * PRM[1 * 64 + cs * 8 + e];
;     unpack8(Rw_c, cu); unpack8(Rw_p, pv);
; #pragma unroll
;     for (int e = 0; e < 8; ++e) {
;       float xw = cu[e] + (pv[e] - cu[e]) * PRM[2 * 64 + cs * 8 + e];
;       float ee = ex2(xw * 2.8853900817779268f);
;       t8[e] = 1.f - 2.f * frcp(ee + 1.f);
;     }
;     *(uint4*)(A1 + (0 * 32 + tt) * 72 + cs * 8) = pack8(t8);
;     unpack8(Ra_c, cu); unpack8(Ra_p, pv);
; #pragma unroll
;     for (int e = 0; e < 8; ++e) t8[e] = cu[e] + (pv[e] - cu[e]) * PRM[3 * 64 + cs * 8 + e];
;     *(uint4*)(A1 + (1 * 32 + tt) * 72 + cs * 8) = pack8(t8);
;     unpack8(Rv_c, cu); unpack8(Rv_p, pv);
;     float v8[8];
; #pragma unroll
;     for (int e = 0; e < 8; ++e) v8[e] = cu[e] + (pv[e] - cu[e]) * PRM[9 * 64 + c4 * 8 + e];
;     *(float4*)(Vst + tt * 32 + c4 * 8) = make_float4(v8[0], v8[1], v8[2], v8[3]);
;     *(float4*)(Vst + tt * 32 + c4 * 8 + 4) = make_float4(v8[4], v8[5], v8[6], v8[7]);
;   };
	v_lshlrev_b32_e32 v156, 16, v20
	v_and_b32_e32 v157, 0xffff0000, v20
	v_lshlrev_b32_e32 v132, 16, v21
	v_and_b32_e32 v133, 0xffff0000, v21
	v_pk_add_f32 v[20:21], v[124:125], v[120:121] neg_lo:[0,1] neg_hi:[0,1]
	s_bitcmp1_b32 s30, 0
	v_pk_fma_f32 v[94:95], v[20:21], v[190:191], v[120:121]
	v_pk_add_f32 v[16:17], v[122:123], v[118:119] neg_lo:[0,1] neg_hi:[0,1]
	v_add_f32_e32 v46, 1.0, v46
	v_pk_fma_f32 v[92:93], v[16:17], v[192:193], v[118:119]
	s_cselect_b32 s18, 0xa000, 0
	s_lshl_b32 s35, s31, 12
	v_rcp_f32_e32 v46, v46
	s_add_i32 s35, s35, 0x14000
	v_lshlrev_b32_e32 v107, 2, v134
	v_pk_add_f32 v[20:21], v[44:45], v[54:55] neg_lo:[0,1] neg_hi:[0,1]
	v_add_u32_e32 v150, s35, v107
	v_pk_fma_f32 v[90:91], v[20:21], v[200:201], v[54:55]
	v_pk_add_f32 v[16:17], v[42:43], v[40:41] neg_lo:[0,1] neg_hi:[0,1]
	ds_read_b32 v106, v150
	v_pk_fma_f32 v[88:89], v[16:17], v[202:203], v[40:41]
	v_pk_fma_f32 v[46:47], v[46:47], 2.0, 1.0 op_sel_hi:[1,0,0] neg_lo:[1,0,0] neg_hi:[1,0,0]
	v_pk_add_f32 v[20:21], v[116:117], v[112:113] neg_lo:[0,1] neg_hi:[0,1]
	v_cvt_pk_bf16_f32 v128, v46, v47
	ds_write_b64 v138, v[128:129]
	v_pk_fma_f32 v[20:21], v[20:21], v[240:241], v[112:113]
	v_pk_add_f32 v[16:17], v[114:115], v[110:111] neg_lo:[0,1] neg_hi:[0,1]
	v_lshlrev_b32_e32 v46, 16, v22
	v_and_b32_e32 v47, 0xffff0000, v22
	v_lshlrev_b32_e32 v38, 16, v23
	v_and_b32_e32 v39, 0xffff0000, v23
	v_pk_fma_f32 v[22:23], v[16:17], v[242:243], v[110:111]
	v_pk_add_f32 v[16:17], v[52:53], v[108:109] neg_lo:[0,1] neg_hi:[0,1]
	v_lshlrev_b32_e32 v18, 16, v24
	v_pk_fma_f32 v[16:17], v[16:17], v[176:177], v[108:109]
	v_and_b32_e32 v19, 0xffff0000, v24
	v_lshlrev_b32_e32 v40, 16, v28
	v_and_b32_e32 v41, 0xffff0000, v28
	v_pk_add_f32 v[40:41], v[40:41], v[18:19] neg_lo:[0,1] neg_hi:[0,1]
	v_lshlrev_b32_e32 v24, 16, v25
	v_pk_fma_f32 v[18:19], v[40:41], v[204:205], v[18:19]
	v_lshlrev_b32_e32 v40, 16, v26
	v_and_b32_e32 v41, 0xffff0000, v26
	v_lshlrev_b32_e32 v42, 16, v30
	v_and_b32_e32 v43, 0xffff0000, v30
	v_pk_add_f32 v[42:43], v[42:43], v[40:41] neg_lo:[0,1] neg_hi:[0,1]
	v_cvt_pk_bf16_f32 v18, v18, v19
	v_pk_fma_f32 v[40:41], v[42:43], v[234:235], v[40:41]
	ds_write_b32 v138, v18 offset:4608
	v_cvt_pk_bf16_f32 v30, v40, v41
	v_accvgpr_read_b32 v40, a42
	v_accvgpr_read_b32 v41, a43
	v_pk_add_f32 v[18:19], v[50:51], v[48:49] neg_lo:[0,1] neg_hi:[0,1]
	ds_write_b64 v138, v[154:155] offset:8
	v_and_b32_e32 v25, 0xffff0000, v25
	v_lshlrev_b32_e32 v28, 16, v29
	v_pk_fma_f32 v[18:19], v[18:19], v[40:41], v[48:49]
	v_accvgpr_read_b32 v40, a44
	v_accvgpr_read_b32 v41, a45
	v_accvgpr_read_b32 v42, a46
	v_accvgpr_read_b32 v43, a47
	v_and_b32_e32 v29, 0xffff0000, v29
	v_pk_add_f32 v[28:29], v[28:29], v[24:25] neg_lo:[0,1] neg_hi:[0,1]
	v_lshlrev_b32_e32 v26, 16, v27
	v_pk_fma_f32 v[24:25], v[28:29], v[40:41], v[24:25]
	v_and_b32_e32 v27, 0xffff0000, v27
	v_lshlrev_b32_e32 v28, 16, v31
	v_and_b32_e32 v29, 0xffff0000, v31
	v_pk_add_f32 v[28:29], v[28:29], v[26:27] neg_lo:[0,1] neg_hi:[0,1]
	v_cvt_pk_bf16_f32 v24, v24, v25
	v_pk_fma_f32 v[26:27], v[28:29], v[42:43], v[26:27]
	v_pk_add_f32 v[40:41], v[156:157], v[130:131] neg_lo:[0,1] neg_hi:[0,1]
	v_cvt_pk_bf16_f32 v25, v26, v27
	ds_write_b32 v138, v25 offset:4620
	v_add_u32_e32 v25, 0x1204, v138
	ds_write2_b32 v25, v24, v30 offset1:1
	v_lshl_add_u32 v33, s34, 12, v140
	s_waitcnt lgkmcnt(5)
	v_pk_mul_f32 v[54:55], v[86:87], v[106:107] op_sel_hi:[1,0]
	s_lshl_b32 s36, s19, 12
	v_pk_fma_f32 v[24:25], v[40:41], v[244:245], v[130:131]
	v_pk_add_f32 v[40:41], v[132:133], v[126:127] neg_lo:[0,1] neg_hi:[0,1]
	v_pk_fma_f32 v[14:15], v[14:15], v[78:79], v[54:55]
	v_pk_fma_f32 v[26:27], v[40:41], v[246:247], v[126:127]
	s_nop 1
	ds_write_b128 v33, v[24:27]
	v_pk_add_f32 v[24:25], v[46:47], v[36:37] neg_lo:[0,1] neg_hi:[0,1]
	v_pk_add_f32 v[26:27], v[38:39], v[34:35] neg_lo:[0,1] neg_hi:[0,1]
	v_pk_fma_f32 v[24:25], v[24:25], v[248:249], v[36:37]
	v_pk_fma_f32 v[26:27], v[26:27], v[250:251], v[34:35]
	s_nop 1
	ds_write_b128 v33, v[24:27] offset:16
	ds_read_b128 v[24:27], v149 offset:1280
	ds_read_b128 v[28:31], v149 offset:1296
	ds_read_b128 v[34:37], v149 offset:1536
	ds_read_b128 v[38:41], v149 offset:1552
	ds_read_b128 v[42:45], v149 offset:1792
	ds_read_b128 v[46:49], v149 offset:1808
	ds_read_b128 v[50:53], v149 offset:2048
	ds_read_b128 v[108:111], v149 offset:2064
	ds_read_b128 v[112:115], v149 offset:2304
	ds_read_b128 v[116:119], v149 offset:2320
	ds_read2_b32 v[120:121], v150 offset0:32 offset1:64
	v_pk_fma_f32 v[78:79], v[32:33], v[82:83], v[14:15] op_sel_hi:[0,1,1]
	s_add_i32 s36, s36, 0x17000
	v_add_u32_e32 v151, s36, v107
	v_add_u32_e32 v153, s18, v146
	s_waitcnt lgkmcnt(0)
; DI float red8(float x) { x += dppf(x, 0); x += dppf(x, 1); x += dppf(x, 2); return x; }
; DI void scan_item(const Params& p, int L, int c, int item, char* smem, bool dry) {
;     ...
;   auto steps8 = [&](const float* PA, const float* Vst, float* Yst, int t0) {
; #pragma unroll
;     for (int t8 = 0; t8 < 8; ++t8) {
;       const int t = t0 + t8;
;       const float* pa = PA + (t + 1) * 320 + ks * 8;
;       const float4 xd0 = *(const float4*)(pa), xd1 = *(const float4*)(pa + 4);
;       const float4 xn0 = *(const float4*)(pa + 64), xn1 = *(const float4*)(pa + 68);
;       const float4 xb0 = *(const float4*)(pa + 128), xb1 = *(const float4*)(pa + 132);
;       const float4 xk0 = *(const float4*)(pa + 192), xk1 = *(const float4*)(pa + 196);
;       const float4 xr0 = *(const float4*)(pa + 256), xr1 = *(const float4*)(pa + 260);
;       const float xvv = Vst[(t + 1) * 32 + row32];
;       float sa0 = S[0] * n0.x, sa1 = S[1] * n0.y;
;       sa0 = fmaf(S[2], n0.z, sa0); sa1 = fmaf(S[3], n0.w, sa1);
;       sa0 = fmaf(S[4], n1.x, sa0); sa1 = fmaf(S[5], n1.y, sa1);
;       sa0 = fmaf(S[6], n1.z, sa0); sa1 = fmaf(S[7], n1.w, sa1);
;       float sa = red8(sa0 + sa1);
;       S[0] = fmaf(sa, b0.x, fmaf(S[0], d0.x, vv * k0.x)); S[1] = fmaf(sa, b0.y, fmaf(S[1], d0.y, vv * k0.y));
;       S[2] = fmaf(sa, b0.z, fmaf(S[2], d0.z, vv * k0.z)); S[3] = fmaf(sa, b0.w, fmaf(S[3], d0.w, vv * k0.w));
;       S[4] = fmaf(sa, b1.x, fmaf(S[4], d1.x, vv * k1.x)); S[5] = fmaf(sa, b1.y, fmaf(S[5], d1.y, vv * k1.y));
;       S[6] = fmaf(sa, b1.z, fmaf(S[6], d1.z, vv * k1.z)); S[7] = fmaf(sa, b1.w, fmaf(S[7], d1.w, vv * k1.w));
;       float y0 = S[0] * r0.x, y1 = S[1] * r0.y;
;       y0 = fmaf(S[2], r0.z, y0); y1 = fmaf(S[3], r0.w, y1);
;       y0 = fmaf(S[4], r1.x, y0); y1 = fmaf(S[5], r1.y, y1);
;       y0 = fmaf(S[6], r1.z, y0); y1 = fmaf(S[7], r1.w, y1);
;       float y = red8(y0 + y1);
;       Yst[t * 32 + row32] = y;
;       d0 = xd0; d1 = xd1; n0 = xn0; n1 = xn1; b0 = xb0; b1 = xb1; k0 = xk0; k1 = xk1; r0 = xr0; r1 = xr1; vv = xvv;
;     }
	v_pk_mul_f32 v[14:15], v[110:111], v[120:121] op_sel_hi:[1,0]
	s_mov_b64 s[18:19], 0
	v_pk_fma_f32 v[82:83], v[78:79], v[30:31], v[14:15]
	v_pk_mul_f32 v[14:15], v[84:85], v[106:107] op_sel_hi:[1,0]
	s_nop 0
	v_pk_fma_f32 v[12:13], v[12:13], v[76:77], v[14:15]
	s_nop 0
	v_pk_fma_f32 v[76:77], v[32:33], v[80:81], v[12:13] op_sel_hi:[0,1,1]
	v_pk_mul_f32 v[12:13], v[108:109], v[120:121] op_sel_hi:[1,0]
	s_nop 0
	v_pk_fma_f32 v[80:81], v[76:77], v[28:29], v[12:13]
	v_pk_mul_f32 v[12:13], v[74:75], v[106:107] op_sel_hi:[1,0]
	s_nop 0
	v_pk_fma_f32 v[10:11], v[10:11], v[66:67], v[12:13]
	s_nop 0
	v_pk_fma_f32 v[74:75], v[32:33], v[70:71], v[10:11] op_sel_hi:[0,1,1]
	v_pk_mul_f32 v[10:11], v[52:53], v[120:121] op_sel_hi:[1,0]
	s_nop 0
	v_pk_fma_f32 v[84:85], v[74:75], v[26:27], v[10:11]
	v_pk_mul_f32 v[10:11], v[72:73], v[106:107] op_sel_hi:[1,0]
	s_nop 0
	v_pk_fma_f32 v[8:9], v[8:9], v[64:65], v[10:11]
	s_nop 0
	v_pk_fma_f32 v[32:33], v[32:33], v[68:69], v[8:9] op_sel_hi:[0,1,1]
	v_pk_mul_f32 v[10:11], v[60:61], v[32:33]
	v_pk_mul_f32 v[8:9], v[50:51], v[120:121] op_sel_hi:[1,0]
	v_pk_fma_f32 v[86:87], v[32:33], v[24:25], v[8:9]
	v_pk_fma_f32 v[10:11], v[74:75], v[62:63], v[10:11]
	v_pk_mul_f32 v[32:33], v[34:35], v[32:33]
	v_pk_fma_f32 v[10:11], v[76:77], v[56:57], v[10:11]
	v_pk_fma_f32 v[32:33], v[74:75], v[36:37], v[32:33]
	v_pk_fma_f32 v[10:11], v[78:79], v[58:59], v[10:11]
	v_pk_fma_f32 v[32:33], v[76:77], v[38:39], v[32:33]
	v_add_f32_e32 v8, v10, v11
	v_pk_fma_f32 v[32:33], v[78:79], v[40:41], v[32:33]
	s_nop 0
	v_add_f32_dpp v8, v8, v8 quad_perm:[1,0,3,2] row_mask:0xf bank_mask:0xf bound_ctrl:1
	v_add_f32_e32 v32, v33, v32
	s_nop 0
	v_add_f32_dpp v8, v8, v8 quad_perm:[2,3,0,1] row_mask:0xf bank_mask:0xf bound_ctrl:1
	v_add_f32_dpp v32, v32, v32 quad_perm:[1,0,3,2] row_mask:0xf bank_mask:0xf bound_ctrl:1
	s_nop 0
	v_add_f32_dpp v8, v8, v8 row_half_mirror row_mask:0xf bank_mask:0xf bound_ctrl:1
	v_add_f32_dpp v32, v32, v32 quad_perm:[2,3,0,1] row_mask:0xf bank_mask:0xf bound_ctrl:1
	ds_write_b32 v151, v8
	ds_read_b128 v[8:11], v149 offset:2560
	ds_read_b128 v[12:15], v149 offset:2576
	ds_read_b128 v[24:27], v149 offset:2816
	ds_read_b128 v[28:31], v149 offset:2832
	ds_read_b128 v[50:53], v149 offset:3072
	ds_read_b128 v[54:57], v149 offset:3088
	ds_read_b128 v[58:61], v149 offset:3328
	ds_read_b128 v[62:65], v149 offset:3344
	ds_read_b128 v[66:69], v149 offset:3584
	ds_read_b128 v[70:73], v149 offset:3600
	v_add_f32_dpp v32, v32, v32 row_half_mirror row_mask:0xf bank_mask:0xf bound_ctrl:1
	v_pk_fma_f32 v[86:87], v[32:33], v[42:43], v[86:87] op_sel_hi:[0,1,1]
	v_pk_fma_f32 v[122:123], v[32:33], v[44:45], v[84:85] op_sel_hi:[0,1,1]
	s_waitcnt lgkmcnt(7)
	v_pk_mul_f32 v[24:25], v[24:25], v[86:87]
	v_pk_fma_f32 v[124:125], v[32:33], v[46:47], v[80:81] op_sel_hi:[0,1,1]
	v_pk_fma_f32 v[24:25], v[122:123], v[26:27], v[24:25]
	v_pk_fma_f32 v[48:49], v[32:33], v[48:49], v[82:83] op_sel_hi:[0,1,1]
	v_pk_mul_f32 v[32:33], v[112:113], v[86:87]
	s_waitcnt lgkmcnt(6)
	v_pk_fma_f32 v[24:25], v[124:125], v[28:29], v[24:25]
	v_pk_fma_f32 v[32:33], v[122:123], v[114:115], v[32:33]
	v_pk_fma_f32 v[24:25], v[48:49], v[30:31], v[24:25]
	v_pk_fma_f32 v[32:33], v[124:125], v[116:117], v[32:33]
	v_add_f32_e32 v24, v25, v24
	v_pk_fma_f32 v[32:33], v[48:49], v[118:119], v[32:33]
	s_nop 0
	v_add_f32_dpp v24, v24, v24 quad_perm:[1,0,3,2] row_mask:0xf bank_mask:0xf bound_ctrl:1
	v_mov_b32_e32 v26, v121
	v_add_f32_e32 v32, v32, v33
	v_add_f32_dpp v24, v24, v24 quad_perm:[2,3,0,1] row_mask:0xf bank_mask:0xf bound_ctrl:1
	s_waitcnt lgkmcnt(3)
	v_pk_mul_f32 v[28:29], v[58:59], v[26:27] op_sel_hi:[1,0]
	v_add_f32_dpp v32, v32, v32 quad_perm:[1,0,3,2] row_mask:0xf bank_mask:0xf bound_ctrl:1
	v_add_f32_dpp v24, v24, v24 row_half_mirror row_mask:0xf bank_mask:0xf bound_ctrl:1
	v_pk_fma_f32 v[8:9], v[86:87], v[8:9], v[28:29]
	v_add_f32_dpp v32, v32, v32 quad_perm:[2,3,0,1] row_mask:0xf bank_mask:0xf bound_ctrl:1
	v_pk_fma_f32 v[86:87], v[24:25], v[50:51], v[8:9] op_sel_hi:[0,1,1]
	v_pk_mul_f32 v[8:9], v[60:61], v[26:27] op_sel_hi:[1,0]
	v_add_f32_dpp v32, v32, v32 row_half_mirror row_mask:0xf bank_mask:0xf bound_ctrl:1
	v_pk_fma_f32 v[8:9], v[122:123], v[10:11], v[8:9]
	ds_write_b32 v151, v32 offset:128
	v_pk_fma_f32 v[120:121], v[24:25], v[52:53], v[8:9] op_sel_hi:[0,1,1]
	s_waitcnt lgkmcnt(3)
	v_pk_mul_f32 v[8:9], v[62:63], v[26:27] op_sel_hi:[1,0]
	ds_read_b128 v[32:35], v149 offset:3840
	ds_read_b128 v[36:39], v149 offset:3856
	ds_read_b128 v[40:43], v149 offset:4096
	ds_read_b128 v[44:47], v149 offset:4112
	ds_read_b128 v[74:77], v149 offset:4352
	ds_read_b128 v[78:81], v149 offset:4368
	ds_read_b128 v[82:85], v149 offset:4608
	ds_read_b128 v[106:109], v149 offset:4624
	ds_read_b128 v[110:113], v149 offset:4864
	ds_read_b128 v[114:117], v149 offset:4880
	ds_read2_b32 v[118:119], v150 offset0:96 offset1:128
	v_pk_fma_f32 v[8:9], v[124:125], v[12:13], v[8:9]
	s_waitcnt lgkmcnt(8)
	v_pk_mul_f32 v[40:41], v[40:41], v[86:87]
	v_pk_fma_f32 v[122:123], v[24:25], v[54:55], v[8:9] op_sel_hi:[0,1,1]
	v_pk_mul_f32 v[8:9], v[64:65], v[26:27] op_sel_hi:[1,0]
	v_pk_fma_f32 v[40:41], v[120:121], v[42:43], v[40:41]
	v_pk_fma_f32 v[8:9], v[48:49], v[14:15], v[8:9]
	s_waitcnt lgkmcnt(7)
	v_pk_fma_f32 v[40:41], v[122:123], v[44:45], v[40:41]
	v_pk_fma_f32 v[124:125], v[24:25], v[56:57], v[8:9] op_sel_hi:[0,1,1]
	v_pk_fma_f32 v[40:41], v[124:125], v[46:47], v[40:41]
	v_add_f32_e32 v40, v41, v40
	v_pk_mul_f32 v[8:9], v[66:67], v[86:87]
	s_waitcnt lgkmcnt(0)
; DI float red8(float x) { x += dppf(x, 0); x += dppf(x, 1); x += dppf(x, 2); return x; }
; DI void scan_item(const Params& p, int L, int c, int item, char* smem, bool dry) {
;     ...
;   auto steps8 = [&](const float* PA, const float* Vst, float* Yst, int t0) {
; #pragma unroll
;     for (int t8 = 0; t8 < 8; ++t8) {
;       const int t = t0 + t8;
;       const float* pa = PA + (t + 1) * 320 + ks * 8;
;       const float4 xd0 = *(const float4*)(pa), xd1 = *(const float4*)(pa + 4);
;       const float4 xn0 = *(const float4*)(pa + 64), xn1 = *(const float4*)(pa + 68);
;       const float4 xb0 = *(const float4*)(pa + 128), xb1 = *(const float4*)(pa + 132);
;       const float4 xk0 = *(const float4*)(pa + 192), xk1 = *(const float4*)(pa + 196);
;       const float4 xr0 = *(const float4*)(pa + 256), xr1 = *(const float4*)(pa + 260);
;       const float xvv = Vst[(t + 1) * 32 + row32];
;       float sa0 = S[0] * n0.x, sa1 = S[1] * n0.y;
;       sa0 = fmaf(S[2], n0.z, sa0); sa1 = fmaf(S[3], n0.w, sa1);
;       sa0 = fmaf(S[4], n1.x, sa0); sa1 = fmaf(S[5], n1.y, sa1);
;       sa0 = fmaf(S[6], n1.z, sa0); sa1 = fmaf(S[7], n1.w, sa1);
;       float sa = red8(sa0 + sa1);
;       S[0] = fmaf(sa, b0.x, fmaf(S[0], d0.x, vv * k0.x)); S[1] = fmaf(sa, b0.y, fmaf(S[1], d0.y, vv * k0.y));
;       S[2] = fmaf(sa, b0.z, fmaf(S[2], d0.z, vv * k0.z)); S[3] = fmaf(sa, b0.w, fmaf(S[3], d0.w, vv * k0.w));
;       S[4] = fmaf(sa, b1.x, fmaf(S[4], d1.x, vv * k1.x)); S[5] = fmaf(sa, b1.y, fmaf(S[5], d1.y, vv * k1.y));
;       S[6] = fmaf(sa, b1.z, fmaf(S[6], d1.z, vv * k1.z)); S[7] = fmaf(sa, b1.w, fmaf(S[7], d1.w, vv * k1.w));
;       float y0 = S[0] * r0.x, y1 = S[1] * r0.y;
;       y0 = fmaf(S[2], r0.z, y0); y1 = fmaf(S[3], r0.w, y1);
;       y0 = fmaf(S[4], r1.x, y0); y1 = fmaf(S[5], r1.y, y1);
;       y0 = fmaf(S[6], r1.z, y0); y1 = fmaf(S[7], r1.w, y1);
;       float y = red8(y0 + y1);
;       Yst[t * 32 + row32] = y;
;       d0 = xd0; d1 = xd1; n0 = xn0; n1 = xn1; b0 = xb0; b1 = xb1; k0 = xk0; k1 = xk1; r0 = xr0; r1 = xr1; vv = xvv;
;     }
	v_pk_mul_f32 v[42:43], v[82:83], v[118:119] op_sel_hi:[1,0]
	v_add_f32_dpp v40, v40, v40 quad_perm:[1,0,3,2] row_mask:0xf bank_mask:0xf bound_ctrl:1
	v_pk_fma_f32 v[8:9], v[120:121], v[68:69], v[8:9]
	s_nop 0
	v_add_f32_dpp v40, v40, v40 quad_perm:[2,3,0,1] row_mask:0xf bank_mask:0xf bound_ctrl:1
	v_pk_fma_f32 v[32:33], v[86:87], v[32:33], v[42:43]
	s_nop 0
	v_add_f32_dpp v40, v40, v40 row_half_mirror row_mask:0xf bank_mask:0xf bound_ctrl:1
	v_pk_fma_f32 v[8:9], v[122:123], v[70:71], v[8:9]
	v_pk_fma_f32 v[126:127], v[40:41], v[74:75], v[32:33] op_sel_hi:[0,1,1]
	v_pk_mul_f32 v[32:33], v[84:85], v[118:119] op_sel_hi:[1,0]
	v_pk_fma_f32 v[8:9], v[124:125], v[72:73], v[8:9]
	v_pk_fma_f32 v[32:33], v[120:121], v[34:35], v[32:33]
	v_add_f32_e32 v8, v8, v9
	v_pk_fma_f32 v[120:121], v[40:41], v[76:77], v[32:33] op_sel_hi:[0,1,1]
	v_pk_mul_f32 v[32:33], v[106:107], v[118:119] op_sel_hi:[1,0]
	v_add_f32_dpp v8, v8, v8 quad_perm:[1,0,3,2] row_mask:0xf bank_mask:0xf bound_ctrl:1
	v_pk_fma_f32 v[32:33], v[122:123], v[36:37], v[32:33]
	s_nop 0
	v_add_f32_dpp v8, v8, v8 quad_perm:[2,3,0,1] row_mask:0xf bank_mask:0xf bound_ctrl:1
	v_pk_fma_f32 v[122:123], v[40:41], v[78:79], v[32:33] op_sel_hi:[0,1,1]
	v_pk_mul_f32 v[32:33], v[108:109], v[118:119] op_sel_hi:[1,0]
	v_add_f32_dpp v8, v8, v8 row_half_mirror row_mask:0xf bank_mask:0xf bound_ctrl:1
	v_pk_fma_f32 v[32:33], v[124:125], v[38:39], v[32:33]
	ds_write_b32 v151, v8 offset:256
	v_pk_fma_f32 v[124:125], v[40:41], v[80:81], v[32:33] op_sel_hi:[0,1,1]
	v_pk_mul_f32 v[32:33], v[110:111], v[126:127]
	ds_read_b128 v[8:11], v149 offset:5120
	ds_read_b128 v[12:15], v149 offset:5136
	ds_read_b128 v[24:27], v149 offset:5376
	ds_read_b128 v[28:31], v149 offset:5392
	ds_read_b128 v[48:51], v149 offset:5632
	ds_read_b128 v[52:55], v149 offset:5648
	ds_read_b128 v[56:59], v149 offset:5888
	ds_read_b128 v[60:63], v149 offset:5904
	ds_read_b128 v[64:67], v149 offset:6144
	ds_read_b128 v[68:71], v149 offset:6160
	v_pk_fma_f32 v[32:33], v[120:121], v[112:113], v[32:33]
	v_pk_fma_f32 v[32:33], v[122:123], v[114:115], v[32:33]
	s_waitcnt lgkmcnt(7)
	v_pk_mul_f32 v[24:25], v[24:25], v[126:127]
	v_pk_fma_f32 v[32:33], v[124:125], v[116:117], v[32:33]
	v_pk_fma_f32 v[24:25], v[120:121], v[26:27], v[24:25]
	v_add_f32_e32 v32, v32, v33
	s_waitcnt lgkmcnt(6)
	v_pk_fma_f32 v[24:25], v[122:123], v[28:29], v[24:25]
	v_mov_b32_e32 v26, v119
	v_add_f32_dpp v32, v32, v32 quad_perm:[1,0,3,2] row_mask:0xf bank_mask:0xf bound_ctrl:1
	v_pk_fma_f32 v[24:25], v[124:125], v[30:31], v[24:25]
	s_waitcnt lgkmcnt(3)
	v_pk_mul_f32 v[28:29], v[56:57], v[26:27] op_sel_hi:[1,0]
	v_add_f32_dpp v32, v32, v32 quad_perm:[2,3,0,1] row_mask:0xf bank_mask:0xf bound_ctrl:1
	v_add_f32_e32 v24, v25, v24
	v_pk_fma_f32 v[8:9], v[126:127], v[8:9], v[28:29]
	v_add_f32_dpp v32, v32, v32 row_half_mirror row_mask:0xf bank_mask:0xf bound_ctrl:1
	v_add_f32_dpp v24, v24, v24 quad_perm:[1,0,3,2] row_mask:0xf bank_mask:0xf bound_ctrl:1
	ds_write_b32 v151, v32 offset:384
	ds_read_b128 v[32:35], v149 offset:6400
	ds_read_b128 v[36:39], v149 offset:6416
	ds_read_b128 v[40:43], v149 offset:6656
	ds_read_b128 v[44:47], v149 offset:6672
	ds_read_b128 v[72:75], v149 offset:6912
	ds_read_b128 v[76:79], v149 offset:6928
	ds_read_b128 v[80:83], v149 offset:7168
	ds_read_b128 v[84:87], v149 offset:7184
	ds_read_b128 v[106:109], v149 offset:7424
	ds_read_b128 v[110:113], v149 offset:7440
	ds_read2_b32 v[128:129], v150 offset0:160 offset1:192
	v_add_f32_dpp v24, v24, v24 quad_perm:[2,3,0,1] row_mask:0xf bank_mask:0xf bound_ctrl:1
	v_pk_mul_f32 v[28:29], v[58:59], v[26:27] op_sel_hi:[1,0]
	s_nop 0
	v_add_f32_dpp v24, v24, v24 row_half_mirror row_mask:0xf bank_mask:0xf bound_ctrl:1
	v_pk_fma_f32 v[8:9], v[24:25], v[48:49], v[8:9] op_sel_hi:[0,1,1]
	v_pk_fma_f32 v[10:11], v[120:121], v[10:11], v[28:29]
	s_waitcnt lgkmcnt(13)
	v_mul_f32_e32 v25, v64, v8
	v_pk_mul_f32 v[28:29], v[60:61], v[26:27] op_sel_hi:[1,0]
	v_pk_fma_f32 v[114:115], v[24:25], v[50:51], v[10:11] op_sel_hi:[0,1,1]
	v_pk_fma_f32 v[12:13], v[122:123], v[12:13], v[28:29]
	v_pk_mul_f32 v[26:27], v[62:63], v[26:27] op_sel_hi:[1,0]
	v_fmac_f32_e32 v25, v114, v66
	v_pk_fma_f32 v[14:15], v[124:125], v[14:15], v[26:27]
	v_mul_f32_e32 v28, v65, v9
	s_waitcnt lgkmcnt(0)
	v_pk_mul_f32 v[26:27], v[80:81], v[128:129] op_sel_hi:[1,0]
	v_pk_fma_f32 v[116:117], v[24:25], v[52:53], v[12:13] op_sel_hi:[0,1,1]
	v_pk_fma_f32 v[80:81], v[8:9], v[32:33], v[26:27]
	v_pk_mul_f32 v[10:11], v[82:83], v[128:129] op_sel_hi:[1,0]
	v_fmac_f32_e32 v28, v115, v67
	v_fmac_f32_e32 v25, v116, v68
	v_pk_mul_f32 v[8:9], v[40:41], v[8:9]
	v_pk_fma_f32 v[82:83], v[114:115], v[34:35], v[10:11]
	v_pk_mul_f32 v[10:11], v[84:85], v[128:129] op_sel_hi:[1,0]
	v_fmac_f32_e32 v28, v117, v69
	v_pk_fma_f32 v[14:15], v[24:25], v[54:55], v[14:15] op_sel_hi:[0,1,1]
	v_pk_fma_f32 v[8:9], v[114:115], v[42:43], v[8:9]
	v_pk_fma_f32 v[84:85], v[116:117], v[36:37], v[10:11]
	v_pk_mul_f32 v[10:11], v[86:87], v[128:129] op_sel_hi:[1,0]
	v_fmac_f32_e32 v25, v14, v70
	v_fmac_f32_e32 v28, v15, v71
	v_pk_fma_f32 v[8:9], v[116:117], v[44:45], v[8:9]
	v_pk_fma_f32 v[68:69], v[14:15], v[38:39], v[10:11]
	v_add_f32_e32 v10, v25, v28
	v_pk_fma_f32 v[8:9], v[14:15], v[46:47], v[8:9]
	v_add_u32_e32 v128, 0x400, v150
	v_add_f32_dpp v10, v10, v10 quad_perm:[1,0,3,2] row_mask:0xf bank_mask:0xf bound_ctrl:1
	v_add_f32_e32 v8, v9, v8
	s_nop 0
	v_add_f32_dpp v10, v10, v10 quad_perm:[2,3,0,1] row_mask:0xf bank_mask:0xf bound_ctrl:1
	v_add_f32_dpp v8, v8, v8 quad_perm:[1,0,3,2] row_mask:0xf bank_mask:0xf bound_ctrl:1
	s_nop 0
	v_add_f32_dpp v10, v10, v10 row_half_mirror row_mask:0xf bank_mask:0xf bound_ctrl:1
	v_add_f32_dpp v8, v8, v8 quad_perm:[2,3,0,1] row_mask:0xf bank_mask:0xf bound_ctrl:1
	ds_write_b32 v151, v10 offset:512
	ds_read_b128 v[10:13], v149 offset:7680
	ds_read_b128 v[24:27], v149 offset:7696
	ds_read_b128 v[28:31], v149 offset:7936
	ds_read_b128 v[32:35], v149 offset:7952
	ds_read_b128 v[36:39], v149 offset:8192
	ds_read_b128 v[48:51], v149 offset:8208
	ds_read_b128 v[52:55], v149 offset:8448
	ds_read_b128 v[56:59], v149 offset:8464
	ds_read_b128 v[60:63], v149 offset:8704
	ds_read_b128 v[64:67], v149 offset:8720
	v_add_f32_dpp v8, v8, v8 row_half_mirror row_mask:0xf bank_mask:0xf bound_ctrl:1
	v_pk_fma_f32 v[14:15], v[8:9], v[72:73], v[80:81] op_sel_hi:[0,1,1]
	v_pk_fma_f32 v[118:119], v[8:9], v[74:75], v[82:83] op_sel_hi:[0,1,1]
	s_waitcnt lgkmcnt(7)
; DI float red8(float x) { x += dppf(x, 0); x += dppf(x, 1); x += dppf(x, 2); return x; }
; DI void scan_item(const Params& p, int L, int c, int item, char* smem, bool dry) {
;     ...
;   auto steps8 = [&](const float* PA, const float* Vst, float* Yst, int t0) {
; #pragma unroll
;     for (int t8 = 0; t8 < 8; ++t8) {
;       const int t = t0 + t8;
;       const float* pa = PA + (t + 1) * 320 + ks * 8;
;       const float4 xd0 = *(const float4*)(pa), xd1 = *(const float4*)(pa + 4);
;       const float4 xn0 = *(const float4*)(pa + 64), xn1 = *(const float4*)(pa + 68);
;       const float4 xb0 = *(const float4*)(pa + 128), xb1 = *(const float4*)(pa + 132);
;       const float4 xk0 = *(const float4*)(pa + 192), xk1 = *(const float4*)(pa + 196);
;       const float4 xr0 = *(const float4*)(pa + 256), xr1 = *(const float4*)(pa + 260);
;       const float xvv = Vst[(t + 1) * 32 + row32];
;       float sa0 = S[0] * n0.x, sa1 = S[1] * n0.y;
;       sa0 = fmaf(S[2], n0.z, sa0); sa1 = fmaf(S[3], n0.w, sa1);
;       sa0 = fmaf(S[4], n1.x, sa0); sa1 = fmaf(S[5], n1.y, sa1);
;       sa0 = fmaf(S[6], n1.z, sa0); sa1 = fmaf(S[7], n1.w, sa1);
;       float sa = red8(sa0 + sa1);
;       S[0] = fmaf(sa, b0.x, fmaf(S[0], d0.x, vv * k0.x)); S[1] = fmaf(sa, b0.y, fmaf(S[1], d0.y, vv * k0.y));
;       S[2] = fmaf(sa, b0.z, fmaf(S[2], d0.z, vv * k0.z)); S[3] = fmaf(sa, b0.w, fmaf(S[3], d0.w, vv * k0.w));
;       S[4] = fmaf(sa, b1.x, fmaf(S[4], d1.x, vv * k1.x)); S[5] = fmaf(sa, b1.y, fmaf(S[5], d1.y, vv * k1.y));
;       S[6] = fmaf(sa, b1.z, fmaf(S[6], d1.z, vv * k1.z)); S[7] = fmaf(sa, b1.w, fmaf(S[7], d1.w, vv * k1.w));
;       float y0 = S[0] * r0.x, y1 = S[1] * r0.y;
;       y0 = fmaf(S[2], r0.z, y0); y1 = fmaf(S[3], r0.w, y1);
;       y0 = fmaf(S[4], r1.x, y0); y1 = fmaf(S[5], r1.y, y1);
;       y0 = fmaf(S[6], r1.z, y0); y1 = fmaf(S[7], r1.w, y1);
;       float y = red8(y0 + y1);
;       Yst[t * 32 + row32] = y;
;       d0 = xd0; d1 = xd1; n0 = xn0; n1 = xn1; b0 = xb0; b1 = xb1; k0 = xk0; k1 = xk1; r0 = xr0; r1 = xr1; vv = xvv;
;     }
	v_pk_mul_f32 v[28:29], v[28:29], v[14:15]
	v_pk_fma_f32 v[120:121], v[8:9], v[76:77], v[84:85] op_sel_hi:[0,1,1]
	v_pk_fma_f32 v[28:29], v[118:119], v[30:31], v[28:29]
	v_pk_fma_f32 v[122:123], v[8:9], v[78:79], v[68:69] op_sel_hi:[0,1,1]
	v_pk_mul_f32 v[8:9], v[106:107], v[14:15]
	s_waitcnt lgkmcnt(6)
	v_pk_fma_f32 v[28:29], v[120:121], v[32:33], v[28:29]
	v_pk_fma_f32 v[8:9], v[118:119], v[108:109], v[8:9]
	v_pk_fma_f32 v[28:29], v[122:123], v[34:35], v[28:29]
	v_pk_fma_f32 v[8:9], v[120:121], v[110:111], v[8:9]
	v_add_f32_e32 v28, v29, v28
	v_pk_fma_f32 v[8:9], v[122:123], v[112:113], v[8:9]
	s_nop 0
	v_add_f32_dpp v28, v28, v28 quad_perm:[1,0,3,2] row_mask:0xf bank_mask:0xf bound_ctrl:1
	v_mov_b32_e32 v30, v129
	v_add_f32_e32 v8, v8, v9
	v_add_f32_dpp v28, v28, v28 quad_perm:[2,3,0,1] row_mask:0xf bank_mask:0xf bound_ctrl:1
	s_waitcnt lgkmcnt(3)
	v_pk_mul_f32 v[32:33], v[52:53], v[30:31] op_sel_hi:[1,0]
	v_add_f32_dpp v8, v8, v8 quad_perm:[1,0,3,2] row_mask:0xf bank_mask:0xf bound_ctrl:1
	v_add_f32_dpp v28, v28, v28 row_half_mirror row_mask:0xf bank_mask:0xf bound_ctrl:1
	v_pk_fma_f32 v[10:11], v[14:15], v[10:11], v[32:33]
	v_add_f32_dpp v8, v8, v8 quad_perm:[2,3,0,1] row_mask:0xf bank_mask:0xf bound_ctrl:1
	v_pk_fma_f32 v[14:15], v[28:29], v[36:37], v[10:11] op_sel_hi:[0,1,1]
	v_pk_mul_f32 v[10:11], v[54:55], v[30:31] op_sel_hi:[1,0]
	v_add_f32_dpp v8, v8, v8 row_half_mirror row_mask:0xf bank_mask:0xf bound_ctrl:1
	v_pk_fma_f32 v[10:11], v[118:119], v[12:13], v[10:11]
	ds_write_b32 v151, v8 offset:640
	v_pk_fma_f32 v[118:119], v[28:29], v[38:39], v[10:11] op_sel_hi:[0,1,1]
	s_waitcnt lgkmcnt(3)
	v_pk_mul_f32 v[10:11], v[56:57], v[30:31] op_sel_hi:[1,0]
	ds_read_b128 v[40:43], v149 offset:8960
	ds_read_b128 v[44:47], v149 offset:8976
	ds_read_b128 v[68:71], v149 offset:9216
	ds_read_b128 v[72:75], v149 offset:9232
	ds_read_b128 v[76:79], v149 offset:9472
	ds_read_b128 v[80:83], v149 offset:9488
	ds_read_b128 v[84:87], v149 offset:9728
	ds_read_b128 v[106:109], v149 offset:9744
	ds_read_b128 v[110:113], v149 offset:9984
	ds_read_b128 v[114:117], v149 offset:10000
	v_add_u32_e32 v8, 0x200, v150
	v_pk_fma_f32 v[10:11], v[120:121], v[24:25], v[10:11]
	ds_read2_b32 v[8:9], v8 offset0:96 offset1:128
	v_pk_fma_f32 v[120:121], v[28:29], v[48:49], v[10:11] op_sel_hi:[0,1,1]
	v_pk_mul_f32 v[10:11], v[58:59], v[30:31] op_sel_hi:[1,0]
	s_waitcnt lgkmcnt(8)
	v_pk_mul_f32 v[68:69], v[68:69], v[14:15]
	v_pk_fma_f32 v[10:11], v[122:123], v[26:27], v[10:11]
	v_pk_fma_f32 v[68:69], v[118:119], v[70:71], v[68:69]
	v_pk_fma_f32 v[122:123], v[28:29], v[50:51], v[10:11] op_sel_hi:[0,1,1]
	s_waitcnt lgkmcnt(7)
	v_pk_fma_f32 v[68:69], v[120:121], v[72:73], v[68:69]
	s_waitcnt lgkmcnt(0)
	v_pk_mul_f32 v[70:71], v[84:85], v[8:9] op_sel_hi:[1,0]
	v_pk_fma_f32 v[68:69], v[122:123], v[74:75], v[68:69]
	v_add_f32_e32 v68, v69, v68
	v_pk_mul_f32 v[10:11], v[60:61], v[14:15]
	v_pk_fma_f32 v[14:15], v[14:15], v[40:41], v[70:71]
	v_add_f32_dpp v68, v68, v68 quad_perm:[1,0,3,2] row_mask:0xf bank_mask:0xf bound_ctrl:1
	v_pk_mul_f32 v[40:41], v[86:87], v[8:9] op_sel_hi:[1,0]
	s_nop 0
	v_add_f32_dpp v68, v68, v68 quad_perm:[2,3,0,1] row_mask:0xf bank_mask:0xf bound_ctrl:1
	v_pk_fma_f32 v[40:41], v[118:119], v[42:43], v[40:41]
	v_pk_fma_f32 v[10:11], v[118:119], v[62:63], v[10:11]
	v_add_f32_dpp v68, v68, v68 row_half_mirror row_mask:0xf bank_mask:0xf bound_ctrl:1
	v_pk_fma_f32 v[118:119], v[68:69], v[78:79], v[40:41] op_sel_hi:[0,1,1]
	v_pk_mul_f32 v[40:41], v[106:107], v[8:9] op_sel_hi:[1,0]
	v_pk_fma_f32 v[40:41], v[120:121], v[44:45], v[40:41]
	v_pk_fma_f32 v[10:11], v[120:121], v[64:65], v[10:11]
	v_pk_fma_f32 v[120:121], v[68:69], v[80:81], v[40:41] op_sel_hi:[0,1,1]
	v_pk_mul_f32 v[40:41], v[108:109], v[8:9] op_sel_hi:[1,0]
	v_pk_fma_f32 v[14:15], v[68:69], v[76:77], v[14:15] op_sel_hi:[0,1,1]
	v_pk_fma_f32 v[40:41], v[122:123], v[46:47], v[40:41]
	v_pk_fma_f32 v[10:11], v[122:123], v[66:67], v[10:11]
	v_pk_fma_f32 v[122:123], v[68:69], v[82:83], v[40:41] op_sel_hi:[0,1,1]
	v_mul_f32_e32 v8, v110, v14
	v_mul_f32_e32 v40, v111, v15
	v_fmac_f32_e32 v8, v118, v112
	v_fmac_f32_e32 v40, v119, v113
	v_fmac_f32_e32 v8, v120, v114
	v_fmac_f32_e32 v40, v121, v115
	v_add_f32_e32 v10, v10, v11
	v_fmac_f32_e32 v8, v122, v116
	v_fmac_f32_e32 v40, v123, v117
	v_add_f32_dpp v10, v10, v10 quad_perm:[1,0,3,2] row_mask:0xf bank_mask:0xf bound_ctrl:1
	v_add_f32_e32 v8, v8, v40
	s_nop 0
	v_add_f32_dpp v10, v10, v10 quad_perm:[2,3,0,1] row_mask:0xf bank_mask:0xf bound_ctrl:1
	v_add_f32_dpp v8, v8, v8 quad_perm:[1,0,3,2] row_mask:0xf bank_mask:0xf bound_ctrl:1
	s_nop 0
	v_add_f32_dpp v10, v10, v10 row_half_mirror row_mask:0xf bank_mask:0xf bound_ctrl:1
	v_add_f32_dpp v8, v8, v8 quad_perm:[2,3,0,1] row_mask:0xf bank_mask:0xf bound_ctrl:1
	ds_write_b32 v151, v10 offset:768
	ds_read_b128 v[10:13], v149 offset:10240
	ds_read_b128 v[24:27], v149 offset:10256
	ds_read_b128 v[28:31], v149 offset:10496
	ds_read_b128 v[32:35], v149 offset:10512
	ds_read_b128 v[36:39], v149 offset:10752
	ds_read_b128 v[48:51], v149 offset:10768
	ds_read_b128 v[52:55], v149 offset:11008
	ds_read_b128 v[56:59], v149 offset:11024
	ds_read_b128 v[60:63], v149 offset:11264
	ds_read_b128 v[64:67], v149 offset:11280
	v_add_f32_dpp v8, v8, v8 row_half_mirror row_mask:0xf bank_mask:0xf bound_ctrl:1
	ds_write_b32 v151, v8 offset:896
	s_waitcnt lgkmcnt(0)
	s_barrier
; DI void scan_item(const Params& p, int L, int c, int item, char* smem, bool dry) {
;     ...
;   auto prep3 = [&]() {
;     const int arr = w >> 1, nt = w & 1;
;     f32x16 acc;
; #pragma unroll
;     for (int e = 0; e < 16; ++e) acc[e] = 0.f;
; #pragma unroll
;     for (int k4 = 0; k4 < 4; ++k4) {
;       bf16x8 a = *(const bf16x8*)(A1 + (arr * 32 + r) * 72 + 16 * k4 + 8 * h);
;       bf16x8 bw = *(const bf16x8*)(W2t + (arr * 64 + 32 * nt + r) * 72 + 16 * k4 + 8 * h);
;       acc = MFMA32(a, bw, acc);
;     }
; #pragma unroll
;     for (int e = 0; e < 16; ++e) LO[(arr * 32 + crow(e, h)) * 64 + 32 * nt + r] = acc[e];
;   };
;     ...
;   auto steps8 = [&](const float* PA, const float* Vst, float* Yst, int t0) {
; #pragma unroll
;     for (int t8 = 0; t8 < 8; ++t8) {
;       const int t = t0 + t8;
;       const float* pa = PA + (t + 1) * 320 + ks * 8;
;       const float4 xd0 = *(const float4*)(pa), xd1 = *(const float4*)(pa + 4);
;       const float4 xn0 = *(const float4*)(pa + 64), xn1 = *(const float4*)(pa + 68);
;       const float4 xb0 = *(const float4*)(pa + 128), xb1 = *(const float4*)(pa + 132);
;       const float4 xk0 = *(const float4*)(pa + 192), xk1 = *(const float4*)(pa + 196);
;       const float4 xr0 = *(const float4*)(pa + 256), xr1 = *(const float4*)(pa + 260);
;       const float xvv = Vst[(t + 1) * 32 + row32];
;       float sa0 = S[0] * n0.x, sa1 = S[1] * n0.y;
;       sa0 = fmaf(S[2], n0.z, sa0); sa1 = fmaf(S[3], n0.w, sa1);
;       sa0 = fmaf(S[4], n1.x, sa0); sa1 = fmaf(S[5], n1.y, sa1);
;       sa0 = fmaf(S[6], n1.z, sa0); sa1 = fmaf(S[7], n1.w, sa1);
;       float sa = red8(sa0 + sa1);
;       S[0] = fmaf(sa, b0.x, fmaf(S[0], d0.x, vv * k0.x)); S[1] = fmaf(sa, b0.y, fmaf(S[1], d0.y, vv * k0.y));
;       S[2] = fmaf(sa, b0.z, fmaf(S[2], d0.z, vv * k0.z)); S[3] = fmaf(sa, b0.w, fmaf(S[3], d0.w, vv * k0.w));
;       S[4] = fmaf(sa, b1.x, fmaf(S[4], d1.x, vv * k1.x)); S[5] = fmaf(sa, b1.y, fmaf(S[5], d1.y, vv * k1.y));
;       S[6] = fmaf(sa, b1.z, fmaf(S[6], d1.z, vv * k1.z)); S[7] = fmaf(sa, b1.w, fmaf(S[7], d1.w, vv * k1.w));
;       float y0 = S[0] * r0.x, y1 = S[1] * r0.y;
;       y0 = fmaf(S[2], r0.z, y0); y1 = fmaf(S[3], r0.w, y1);
;       y0 = fmaf(S[4], r1.x, y0); y1 = fmaf(S[5], r1.y, y1);
;       y0 = fmaf(S[6], r1.z, y0); y1 = fmaf(S[7], r1.w, y1);
;       float y = red8(y0 + y1);
;       Yst[t * 32 + row32] = y;
	ds_read_b128 v[40:43], v141
	ds_read_b128 v[44:47], v141 offset:32
	ds_read_b128 v[68:71], v142
	ds_read_b128 v[72:75], v142 offset:32
	s_waitcnt lgkmcnt(1)
	v_mfma_f32_32x32x16_bf16 a[0:15], v[40:43], v[68:71], 0
	v_mul_f32_e64 v28, v28, v14
	v_mul_f32_e64 v29, v29, v15
	v_fma_f32 v28, v118, v30, v28
	v_fma_f32 v29, v119, v31, v29
	v_fma_f32 v28, v120, v32, v28
	v_fma_f32 v29, v121, v33, v29
	v_pk_fma_f32 v[28:29], v[122:123], v[34:35], v[28:29]
	s_waitcnt lgkmcnt(0)
	v_mfma_f32_32x32x16_bf16 a[0:15], v[44:47], v[72:75], a[0:15]
	ds_read_b128 v[40:43], v141 offset:64
	ds_read_b128 v[44:47], v142 offset:64
	v_add_f32_e32 v8, v28, v29
	v_mov_b32_e32 v28, v9
	v_mul_f32_e64 v30, v52, v28
	v_mul_f32_e64 v31, v53, v28
	v_add_f32_dpp v8, v8, v8 quad_perm:[1,0,3,2] row_mask:0xf bank_mask:0xf bound_ctrl:1
	v_pk_fma_f32 v[10:11], v[14:15], v[10:11], v[30:31]
	s_waitcnt lgkmcnt(0)
	v_mfma_f32_32x32x16_bf16 a[0:15], v[40:43], v[44:47], a[0:15]
	ds_read_b128 v[40:43], v141 offset:96
	ds_read_b128 v[44:47], v142 offset:96
	v_add_f32_dpp v8, v8, v8 quad_perm:[2,3,0,1] row_mask:0xf bank_mask:0xf bound_ctrl:1
	s_nop 1
	v_add_f32_dpp v8, v8, v8 row_half_mirror row_mask:0xf bank_mask:0xf bound_ctrl:1
	v_fma_f32 v126, v8, v36, v10
	v_fma_f32 v127, v8, v37, v11
	v_pk_mul_f32 v[10:11], v[54:55], v[28:29] op_sel_hi:[1,0]
	s_waitcnt lgkmcnt(0)
	v_mfma_f32_32x32x16_bf16 a[0:15], v[40:43], v[44:47], a[0:15]
	v_fma_f32 v10, v118, v12, v10
	v_fma_f32 v11, v119, v13, v11
	s_nop 9
	ds_write_b32 v144, a0
	ds_write_b32 v144, a1 offset:256
	ds_write_b32 v144, a2 offset:512
	ds_write_b32 v144, a3 offset:768
	ds_write_b32 v144, a4 offset:2048
	ds_write_b32 v144, a5 offset:2304
	ds_write_b32 v144, a6 offset:2560
	ds_write_b32 v144, a7 offset:2816
	ds_write_b32 v144, a8 offset:4096
	ds_write_b32 v144, a9 offset:4352
	ds_write_b32 v144, a10 offset:4608
	ds_write_b32 v144, a11 offset:4864
	ds_write_b32 v144, a12 offset:6144
	ds_write_b32 v144, a13 offset:6400
	ds_write_b32 v144, a14 offset:6656
	ds_write_b32 v144, a15 offset:6912
	v_pk_fma_f32 v[118:119], v[8:9], v[38:39], v[10:11] op_sel_hi:[0,1,1]
	v_pk_mul_f32 v[10:11], v[56:57], v[28:29] op_sel_hi:[1,0]
	ds_read_b128 v[40:43], v149 offset:11520
	ds_read_b128 v[44:47], v149 offset:11536
	ds_read_b128 v[68:71], v149 offset:11776
	ds_read_b128 v[72:75], v149 offset:11792
	ds_read_b128 v[76:79], v149 offset:12032
	ds_read_b128 v[80:83], v149 offset:12048
	ds_read_b128 v[84:87], v149 offset:12288
	ds_read_b128 v[106:109], v149 offset:12304
	ds_read_b128 v[110:113], v149 offset:12544
	ds_read_b128 v[114:117], v149 offset:12560
	v_pk_fma_f32 v[10:11], v[120:121], v[24:25], v[10:11]
	ds_read2_b32 v[124:125], v128 offset0:32 offset1:64
	v_pk_fma_f32 v[120:121], v[8:9], v[48:49], v[10:11] op_sel_hi:[0,1,1]
	v_pk_mul_f32 v[10:11], v[58:59], v[28:29] op_sel_hi:[1,0]
	s_nop 0
	v_pk_fma_f32 v[10:11], v[122:123], v[26:27], v[10:11]
	s_nop 0
	v_pk_fma_f32 v[122:123], v[8:9], v[50:51], v[10:11] op_sel_hi:[0,1,1]
	v_pk_mul_f32 v[8:9], v[60:61], v[126:127]
	v_pk_fma_f32 v[8:9], v[118:119], v[62:63], v[8:9]
	v_pk_fma_f32 v[8:9], v[120:121], v[64:65], v[8:9]
	s_waitcnt lgkmcnt(8)
	v_pk_mul_f32 v[64:65], v[68:69], v[126:127]
	v_pk_fma_f32 v[64:65], v[118:119], v[70:71], v[64:65]
	v_pk_fma_f32 v[8:9], v[122:123], v[66:67], v[8:9]
	s_waitcnt lgkmcnt(7)
	v_pk_fma_f32 v[64:65], v[120:121], v[72:73], v[64:65]
	s_waitcnt lgkmcnt(0)
	v_pk_mul_f32 v[66:67], v[84:85], v[124:125] op_sel_hi:[1,0]
	v_pk_fma_f32 v[64:65], v[122:123], v[74:75], v[64:65]
	v_pk_fma_f32 v[40:41], v[126:127], v[40:41], v[66:67]
	v_add_f32_e32 v64, v65, v64
	v_add_f32_e32 v8, v8, v9
	s_nop 0
	v_add_f32_dpp v64, v64, v64 quad_perm:[1,0,3,2] row_mask:0xf bank_mask:0xf bound_ctrl:1
	v_add_f32_dpp v8, v8, v8 quad_perm:[1,0,3,2] row_mask:0xf bank_mask:0xf bound_ctrl:1
	s_nop 0
	v_add_f32_dpp v64, v64, v64 quad_perm:[2,3,0,1] row_mask:0xf bank_mask:0xf bound_ctrl:1
	v_add_f32_dpp v8, v8, v8 quad_perm:[2,3,0,1] row_mask:0xf bank_mask:0xf bound_ctrl:1
	s_nop 0
	v_add_f32_dpp v64, v64, v64 row_half_mirror row_mask:0xf bank_mask:0xf bound_ctrl:1
	v_pk_fma_f32 v[126:127], v[64:65], v[76:77], v[40:41] op_sel_hi:[0,1,1]
	v_pk_mul_f32 v[40:41], v[86:87], v[124:125] op_sel_hi:[1,0]
	v_add_f32_dpp v8, v8, v8 row_half_mirror row_mask:0xf bank_mask:0xf bound_ctrl:1
	v_pk_fma_f32 v[40:41], v[118:119], v[42:43], v[40:41]
	ds_write_b32 v151, v8 offset:1024
	v_pk_fma_f32 v[118:119], v[64:65], v[78:79], v[40:41] op_sel_hi:[0,1,1]
	v_pk_mul_f32 v[40:41], v[106:107], v[124:125] op_sel_hi:[1,0]
	ds_read_b128 v[8:11], v149 offset:12800
	ds_read_b128 v[12:15], v149 offset:12816
	ds_read_b128 v[24:27], v149 offset:13056
	ds_read_b128 v[28:31], v149 offset:13072
	ds_read_b128 v[32:35], v149 offset:13312
	ds_read_b128 v[36:39], v149 offset:13328
	ds_read_b128 v[48:51], v149 offset:13568
	ds_read_b128 v[52:55], v149 offset:13584
	ds_read_b128 v[56:59], v149 offset:13824
	ds_read_b128 v[60:63], v149 offset:13840
	v_pk_fma_f32 v[40:41], v[120:121], v[44:45], v[40:41]
	s_waitcnt lgkmcnt(7)
	v_pk_mul_f32 v[24:25], v[24:25], v[126:127]
	v_pk_fma_f32 v[120:121], v[64:65], v[80:81], v[40:41] op_sel_hi:[0,1,1]
	v_pk_mul_f32 v[40:41], v[108:109], v[124:125] op_sel_hi:[1,0]
	v_pk_fma_f32 v[24:25], v[118:119], v[26:27], v[24:25]
	v_pk_fma_f32 v[40:41], v[122:123], v[46:47], v[40:41]
	s_waitcnt lgkmcnt(6)
	v_pk_fma_f32 v[24:25], v[120:121], v[28:29], v[24:25]
	v_pk_fma_f32 v[122:123], v[64:65], v[82:83], v[40:41] op_sel_hi:[0,1,1]
	v_pk_mul_f32 v[40:41], v[110:111], v[126:127]
	v_pk_fma_f32 v[40:41], v[118:119], v[112:113], v[40:41]
	v_pk_fma_f32 v[40:41], v[120:121], v[114:115], v[40:41]
	v_pk_fma_f32 v[40:41], v[122:123], v[116:117], v[40:41]
	v_add_f32_e32 v40, v40, v41
	v_pk_fma_f32 v[24:25], v[122:123], v[30:31], v[24:25]
	v_mov_b32_e32 v26, v125
	v_add_f32_dpp v40, v40, v40 quad_perm:[1,0,3,2] row_mask:0xf bank_mask:0xf bound_ctrl:1
	v_add_f32_e32 v24, v25, v24
	s_waitcnt lgkmcnt(3)
; DI float red8(float x) { x += dppf(x, 0); x += dppf(x, 1); x += dppf(x, 2); return x; }
; DI void scan_item(const Params& p, int L, int c, int item, char* smem, bool dry) {
;     ...
;   auto steps8 = [&](const float* PA, const float* Vst, float* Yst, int t0) {
; #pragma unroll
;     for (int t8 = 0; t8 < 8; ++t8) {
;       const int t = t0 + t8;
;       const float* pa = PA + (t + 1) * 320 + ks * 8;
;       const float4 xd0 = *(const float4*)(pa), xd1 = *(const float4*)(pa + 4);
;       const float4 xn0 = *(const float4*)(pa + 64), xn1 = *(const float4*)(pa + 68);
;       const float4 xb0 = *(const float4*)(pa + 128), xb1 = *(const float4*)(pa + 132);
;       const float4 xk0 = *(const float4*)(pa + 192), xk1 = *(const float4*)(pa + 196);
;       const float4 xr0 = *(const float4*)(pa + 256), xr1 = *(const float4*)(pa + 260);
;       const float xvv = Vst[(t + 1) * 32 + row32];
;       float sa0 = S[0] * n0.x, sa1 = S[1] * n0.y;
;       sa0 = fmaf(S[2], n0.z, sa0); sa1 = fmaf(S[3], n0.w, sa1);
;       sa0 = fmaf(S[4], n1.x, sa0); sa1 = fmaf(S[5], n1.y, sa1);
;       sa0 = fmaf(S[6], n1.z, sa0); sa1 = fmaf(S[7], n1.w, sa1);
;       float sa = red8(sa0 + sa1);
;       S[0] = fmaf(sa, b0.x, fmaf(S[0], d0.x, vv * k0.x)); S[1] = fmaf(sa, b0.y, fmaf(S[1], d0.y, vv * k0.y));
;       S[2] = fmaf(sa, b0.z, fmaf(S[2], d0.z, vv * k0.z)); S[3] = fmaf(sa, b0.w, fmaf(S[3], d0.w, vv * k0.w));
;       S[4] = fmaf(sa, b1.x, fmaf(S[4], d1.x, vv * k1.x)); S[5] = fmaf(sa, b1.y, fmaf(S[5], d1.y, vv * k1.y));
;       S[6] = fmaf(sa, b1.z, fmaf(S[6], d1.z, vv * k1.z)); S[7] = fmaf(sa, b1.w, fmaf(S[7], d1.w, vv * k1.w));
;       float y0 = S[0] * r0.x, y1 = S[1] * r0.y;
;       y0 = fmaf(S[2], r0.z, y0); y1 = fmaf(S[3], r0.w, y1);
;       y0 = fmaf(S[4], r1.x, y0); y1 = fmaf(S[5], r1.y, y1);
;       y0 = fmaf(S[6], r1.z, y0); y1 = fmaf(S[7], r1.w, y1);
;       float y = red8(y0 + y1);
;       Yst[t * 32 + row32] = y;
;       d0 = xd0; d1 = xd1; n0 = xn0; n1 = xn1; b0 = xb0; b1 = xb1; k0 = xk0; k1 = xk1; r0 = xr0; r1 = xr1; vv = xvv;
;     }
	v_pk_mul_f32 v[28:29], v[48:49], v[26:27] op_sel_hi:[1,0]
	v_add_f32_dpp v40, v40, v40 quad_perm:[2,3,0,1] row_mask:0xf bank_mask:0xf bound_ctrl:1
	v_add_f32_dpp v24, v24, v24 quad_perm:[1,0,3,2] row_mask:0xf bank_mask:0xf bound_ctrl:1
	v_pk_mul_f32 v[30:31], v[50:51], v[26:27] op_sel_hi:[1,0]
	v_add_f32_dpp v40, v40, v40 row_half_mirror row_mask:0xf bank_mask:0xf bound_ctrl:1
	ds_write_b32 v151, v40 offset:1152
	ds_read_b128 v[40:43], v149 offset:14080
	ds_read_b128 v[44:47], v149 offset:14096
	ds_read_b128 v[64:67], v149 offset:14336
	ds_read_b128 v[68:71], v149 offset:14352
	ds_read_b128 v[72:75], v149 offset:14592
	ds_read_b128 v[76:79], v149 offset:14608
	ds_read_b128 v[80:83], v149 offset:14848
	ds_read_b128 v[84:87], v149 offset:14864
	ds_read_b128 v[106:109], v149 offset:15104
	ds_read_b128 v[110:113], v149 offset:15120
	ds_read2_b32 v[114:115], v128 offset0:96 offset1:128
	v_add_f32_dpp v24, v24, v24 quad_perm:[2,3,0,1] row_mask:0xf bank_mask:0xf bound_ctrl:1
	s_waitcnt lgkmcnt(14)
	v_pk_mul_f32 v[48:49], v[52:53], v[26:27] op_sel_hi:[1,0]
	v_pk_mul_f32 v[26:27], v[54:55], v[26:27] op_sel_hi:[1,0]
	v_add_f32_dpp v24, v24, v24 row_half_mirror row_mask:0xf bank_mask:0xf bound_ctrl:1
	v_pk_fma_f32 v[10:11], v[118:119], v[10:11], v[30:31]
	v_pk_fma_f32 v[8:9], v[126:127], v[8:9], v[28:29]
	v_pk_fma_f32 v[14:15], v[122:123], v[14:15], v[26:27]
	v_pk_fma_f32 v[118:119], v[24:25], v[34:35], v[10:11] op_sel_hi:[0,1,1]
	s_waitcnt lgkmcnt(0)
	v_pk_mul_f32 v[10:11], v[82:83], v[114:115] op_sel_hi:[1,0]
	v_pk_fma_f32 v[122:123], v[24:25], v[32:33], v[8:9] op_sel_hi:[0,1,1]
	v_pk_fma_f32 v[12:13], v[120:121], v[12:13], v[48:49]
	v_pk_fma_f32 v[82:83], v[118:119], v[42:43], v[10:11]
	v_pk_mul_f32 v[10:11], v[56:57], v[122:123]
	v_pk_fma_f32 v[120:121], v[24:25], v[36:37], v[12:13] op_sel_hi:[0,1,1]
	v_pk_fma_f32 v[10:11], v[118:119], v[58:59], v[10:11]
	v_pk_mul_f32 v[58:59], v[64:65], v[122:123]
	v_pk_fma_f32 v[116:117], v[24:25], v[38:39], v[14:15] op_sel_hi:[0,1,1]
	v_pk_fma_f32 v[10:11], v[120:121], v[60:61], v[10:11]
	v_pk_fma_f32 v[58:59], v[118:119], v[66:67], v[58:59]
	v_pk_mul_f32 v[8:9], v[80:81], v[114:115] op_sel_hi:[1,0]
	v_pk_fma_f32 v[10:11], v[116:117], v[62:63], v[10:11]
	v_pk_fma_f32 v[58:59], v[120:121], v[68:69], v[58:59]
	v_pk_fma_f32 v[56:57], v[122:123], v[40:41], v[8:9]
	v_add_f32_e32 v8, v10, v11
	v_pk_fma_f32 v[58:59], v[116:117], v[70:71], v[58:59]
	v_pk_mul_f32 v[14:15], v[86:87], v[114:115] op_sel_hi:[1,0]
	v_add_f32_dpp v8, v8, v8 quad_perm:[1,0,3,2] row_mask:0xf bank_mask:0xf bound_ctrl:1
	v_add_f32_e32 v58, v59, v58
	v_pk_mul_f32 v[12:13], v[84:85], v[114:115] op_sel_hi:[1,0]
	v_add_f32_dpp v8, v8, v8 quad_perm:[2,3,0,1] row_mask:0xf bank_mask:0xf bound_ctrl:1
	v_add_f32_dpp v58, v58, v58 quad_perm:[1,0,3,2] row_mask:0xf bank_mask:0xf bound_ctrl:1
	v_pk_fma_f32 v[86:87], v[116:117], v[46:47], v[14:15]
	v_add_f32_dpp v8, v8, v8 row_half_mirror row_mask:0xf bank_mask:0xf bound_ctrl:1
	v_add_f32_dpp v58, v58, v58 quad_perm:[2,3,0,1] row_mask:0xf bank_mask:0xf bound_ctrl:1
	ds_write_b32 v151, v8 offset:1280
	v_pk_fma_f32 v[84:85], v[120:121], v[44:45], v[12:13]
	v_add_f32_dpp v58, v58, v58 row_half_mirror row_mask:0xf bank_mask:0xf bound_ctrl:1
	ds_read_b128 v[8:11], v149 offset:15360
	ds_read_b128 v[12:15], v149 offset:15376
	ds_read_b128 v[24:27], v149 offset:15616
	ds_read_b128 v[28:31], v149 offset:15632
	ds_read_b128 v[32:35], v149 offset:15872
	ds_read_b128 v[36:39], v149 offset:15888
	ds_read_b128 v[40:43], v149 offset:16128
	ds_read_b128 v[44:47], v149 offset:16144
	ds_read_b128 v[48:51], v149 offset:16384
	ds_read_b128 v[52:55], v149 offset:16400
	v_pk_fma_f32 v[116:117], v[58:59], v[72:73], v[56:57] op_sel_hi:[0,1,1]
	v_pk_fma_f32 v[118:119], v[58:59], v[74:75], v[82:83] op_sel_hi:[0,1,1]
	s_waitcnt lgkmcnt(7)
	v_pk_mul_f32 v[24:25], v[24:25], v[116:117]
	v_pk_fma_f32 v[120:121], v[58:59], v[76:77], v[84:85] op_sel_hi:[0,1,1]
	v_pk_fma_f32 v[24:25], v[118:119], v[26:27], v[24:25]
	v_pk_fma_f32 v[122:123], v[58:59], v[78:79], v[86:87] op_sel_hi:[0,1,1]
	v_pk_mul_f32 v[56:57], v[106:107], v[116:117]
	s_waitcnt lgkmcnt(6)
	v_pk_fma_f32 v[24:25], v[120:121], v[28:29], v[24:25]
	v_pk_fma_f32 v[56:57], v[118:119], v[108:109], v[56:57]
	v_pk_fma_f32 v[24:25], v[122:123], v[30:31], v[24:25]
	v_pk_fma_f32 v[56:57], v[120:121], v[110:111], v[56:57]
	v_add_f32_e32 v24, v25, v24
	v_pk_fma_f32 v[56:57], v[122:123], v[112:113], v[56:57]
	s_nop 0
	v_add_f32_dpp v24, v24, v24 quad_perm:[1,0,3,2] row_mask:0xf bank_mask:0xf bound_ctrl:1
	v_mov_b32_e32 v26, v115
	v_add_f32_e32 v56, v56, v57
	v_add_f32_dpp v24, v24, v24 quad_perm:[2,3,0,1] row_mask:0xf bank_mask:0xf bound_ctrl:1
	s_waitcnt lgkmcnt(3)
	v_pk_mul_f32 v[28:29], v[40:41], v[26:27] op_sel_hi:[1,0]
	v_add_f32_dpp v56, v56, v56 quad_perm:[1,0,3,2] row_mask:0xf bank_mask:0xf bound_ctrl:1
	v_add_f32_dpp v24, v24, v24 row_half_mirror row_mask:0xf bank_mask:0xf bound_ctrl:1
	v_pk_fma_f32 v[8:9], v[116:117], v[8:9], v[28:29]
	v_add_f32_dpp v56, v56, v56 quad_perm:[2,3,0,1] row_mask:0xf bank_mask:0xf bound_ctrl:1
	v_pk_fma_f32 v[114:115], v[24:25], v[32:33], v[8:9] op_sel_hi:[0,1,1]
	v_pk_mul_f32 v[8:9], v[42:43], v[26:27] op_sel_hi:[1,0]
	v_add_f32_dpp v56, v56, v56 row_half_mirror row_mask:0xf bank_mask:0xf bound_ctrl:1
	v_pk_fma_f32 v[8:9], v[118:119], v[10:11], v[8:9]
	ds_write_b32 v151, v56 offset:1408
	v_pk_fma_f32 v[116:117], v[24:25], v[34:35], v[8:9] op_sel_hi:[0,1,1]
	s_waitcnt lgkmcnt(3)
; DI float red8(float x) { x += dppf(x, 0); x += dppf(x, 1); x += dppf(x, 2); return x; }
; DI void scan_item(const Params& p, int L, int c, int item, char* smem, bool dry) {
;     ...
;   auto steps8 = [&](const float* PA, const float* Vst, float* Yst, int t0) {
; #pragma unroll
;     for (int t8 = 0; t8 < 8; ++t8) {
;       const int t = t0 + t8;
;       const float* pa = PA + (t + 1) * 320 + ks * 8;
;       const float4 xd0 = *(const float4*)(pa), xd1 = *(const float4*)(pa + 4);
;       const float4 xn0 = *(const float4*)(pa + 64), xn1 = *(const float4*)(pa + 68);
;       const float4 xb0 = *(const float4*)(pa + 128), xb1 = *(const float4*)(pa + 132);
;       const float4 xk0 = *(const float4*)(pa + 192), xk1 = *(const float4*)(pa + 196);
;       const float4 xr0 = *(const float4*)(pa + 256), xr1 = *(const float4*)(pa + 260);
;       const float xvv = Vst[(t + 1) * 32 + row32];
;       float sa0 = S[0] * n0.x, sa1 = S[1] * n0.y;
;       sa0 = fmaf(S[2], n0.z, sa0); sa1 = fmaf(S[3], n0.w, sa1);
;       sa0 = fmaf(S[4], n1.x, sa0); sa1 = fmaf(S[5], n1.y, sa1);
;       sa0 = fmaf(S[6], n1.z, sa0); sa1 = fmaf(S[7], n1.w, sa1);
;       float sa = red8(sa0 + sa1);
;       S[0] = fmaf(sa, b0.x, fmaf(S[0], d0.x, vv * k0.x)); S[1] = fmaf(sa, b0.y, fmaf(S[1], d0.y, vv * k0.y));
;       S[2] = fmaf(sa, b0.z, fmaf(S[2], d0.z, vv * k0.z)); S[3] = fmaf(sa, b0.w, fmaf(S[3], d0.w, vv * k0.w));
;       S[4] = fmaf(sa, b1.x, fmaf(S[4], d1.x, vv * k1.x)); S[5] = fmaf(sa, b1.y, fmaf(S[5], d1.y, vv * k1.y));
;       S[6] = fmaf(sa, b1.z, fmaf(S[6], d1.z, vv * k1.z)); S[7] = fmaf(sa, b1.w, fmaf(S[7], d1.w, vv * k1.w));
;       float y0 = S[0] * r0.x, y1 = S[1] * r0.y;
;       y0 = fmaf(S[2], r0.z, y0); y1 = fmaf(S[3], r0.w, y1);
;       y0 = fmaf(S[4], r1.x, y0); y1 = fmaf(S[5], r1.y, y1);
;       y0 = fmaf(S[6], r1.z, y0); y1 = fmaf(S[7], r1.w, y1);
;       float y = red8(y0 + y1);
;       Yst[t * 32 + row32] = y;
;       d0 = xd0; d1 = xd1; n0 = xn0; n1 = xn1; b0 = xb0; b1 = xb1; k0 = xk0; k1 = xk1; r0 = xr0; r1 = xr1; vv = xvv;
;     }
	v_pk_mul_f32 v[8:9], v[44:45], v[26:27] op_sel_hi:[1,0]
	ds_read_b128 v[56:59], v149 offset:16640
	ds_read_b128 v[60:63], v149 offset:16656
	ds_read_b128 v[64:67], v149 offset:16896
	ds_read_b128 v[68:71], v149 offset:16912
	ds_read_b128 v[72:75], v149 offset:17152
	ds_read_b128 v[76:79], v149 offset:17168
	ds_read_b128 v[80:83], v149 offset:17408
	ds_read_b128 v[84:87], v149 offset:17424
	ds_read_b128 v[106:109], v149 offset:17664
	ds_read_b128 v[110:113], v149 offset:17680
	ds_read2_b32 v[124:125], v128 offset0:160 offset1:192
	v_pk_fma_f32 v[8:9], v[120:121], v[12:13], v[8:9]
	s_waitcnt lgkmcnt(8)
	v_pk_mul_f32 v[64:65], v[64:65], v[114:115]
	v_pk_fma_f32 v[118:119], v[24:25], v[36:37], v[8:9] op_sel_hi:[0,1,1]
	v_pk_mul_f32 v[8:9], v[46:47], v[26:27] op_sel_hi:[1,0]
	v_pk_fma_f32 v[64:65], v[116:117], v[66:67], v[64:65]
	v_pk_fma_f32 v[8:9], v[122:123], v[14:15], v[8:9]
	s_waitcnt lgkmcnt(7)
	v_pk_fma_f32 v[64:65], v[118:119], v[68:69], v[64:65]
	v_pk_fma_f32 v[120:121], v[24:25], v[38:39], v[8:9] op_sel_hi:[0,1,1]
	v_pk_mul_f32 v[8:9], v[48:49], v[114:115]
	v_pk_fma_f32 v[8:9], v[116:117], v[50:51], v[8:9]
	v_pk_fma_f32 v[64:65], v[120:121], v[70:71], v[64:65]
	v_pk_fma_f32 v[8:9], v[118:119], v[52:53], v[8:9]
	v_add_f32_e32 v64, v65, v64
	v_pk_fma_f32 v[8:9], v[120:121], v[54:55], v[8:9]
	s_nop 0
	v_add_f32_dpp v64, v64, v64 quad_perm:[1,0,3,2] row_mask:0xf bank_mask:0xf bound_ctrl:1
	v_add_f32_e32 v8, v8, v9
	s_waitcnt lgkmcnt(0)
	v_pk_mul_f32 v[66:67], v[80:81], v[124:125] op_sel_hi:[1,0]
	v_add_f32_dpp v64, v64, v64 quad_perm:[2,3,0,1] row_mask:0xf bank_mask:0xf bound_ctrl:1
	v_add_f32_dpp v8, v8, v8 quad_perm:[1,0,3,2] row_mask:0xf bank_mask:0xf bound_ctrl:1
	v_pk_fma_f32 v[56:57], v[114:115], v[56:57], v[66:67]
	v_add_f32_dpp v64, v64, v64 row_half_mirror row_mask:0xf bank_mask:0xf bound_ctrl:1
	v_add_f32_dpp v8, v8, v8 quad_perm:[2,3,0,1] row_mask:0xf bank_mask:0xf bound_ctrl:1
	v_pk_fma_f32 v[114:115], v[64:65], v[72:73], v[56:57] op_sel_hi:[0,1,1]
	v_pk_mul_f32 v[56:57], v[82:83], v[124:125] op_sel_hi:[1,0]
	v_add_f32_dpp v8, v8, v8 row_half_mirror row_mask:0xf bank_mask:0xf bound_ctrl:1
	v_pk_fma_f32 v[56:57], v[116:117], v[58:59], v[56:57]
	ds_write_b32 v151, v8 offset:1536
	v_pk_fma_f32 v[116:117], v[64:65], v[74:75], v[56:57] op_sel_hi:[0,1,1]
	v_pk_mul_f32 v[56:57], v[84:85], v[124:125] op_sel_hi:[1,0]
	ds_read_b128 v[8:11], v149 offset:17920
	ds_read_b128 v[12:15], v149 offset:17936
	ds_read_b128 v[24:27], v149 offset:18176
	ds_read_b128 v[28:31], v149 offset:18192
	ds_read_b128 v[32:35], v149 offset:18432
	ds_read_b128 v[36:39], v149 offset:18448
	ds_read_b128 v[40:43], v149 offset:18688
	ds_read_b128 v[44:47], v149 offset:18704
	ds_read_b128 v[48:51], v149 offset:18944
	ds_read_b128 v[52:55], v149 offset:18960
	v_pk_fma_f32 v[56:57], v[118:119], v[60:61], v[56:57]
	s_waitcnt lgkmcnt(7)
	v_pk_mul_f32 v[24:25], v[24:25], v[114:115]
	v_pk_fma_f32 v[76:77], v[64:65], v[76:77], v[56:57] op_sel_hi:[0,1,1]
	v_pk_mul_f32 v[56:57], v[86:87], v[124:125] op_sel_hi:[1,0]
	v_pk_fma_f32 v[24:25], v[116:117], v[26:27], v[24:25]
	v_pk_fma_f32 v[56:57], v[120:121], v[62:63], v[56:57]
	s_waitcnt lgkmcnt(6)
	v_pk_fma_f32 v[24:25], v[76:77], v[28:29], v[24:25]
	v_pk_fma_f32 v[86:87], v[64:65], v[78:79], v[56:57] op_sel_hi:[0,1,1]
	v_pk_mul_f32 v[56:57], v[106:107], v[114:115]
	v_pk_fma_f32 v[24:25], v[86:87], v[30:31], v[24:25]
	v_pk_fma_f32 v[56:57], v[116:117], v[108:109], v[56:57]
	v_add_f32_e32 v24, v25, v24
	v_pk_fma_f32 v[56:57], v[76:77], v[110:111], v[56:57]
	s_nop 0
	v_add_f32_dpp v24, v24, v24 quad_perm:[1,0,3,2] row_mask:0xf bank_mask:0xf bound_ctrl:1
	v_mov_b32_e32 v26, v125
	v_pk_fma_f32 v[56:57], v[86:87], v[112:113], v[56:57]
	v_add_f32_dpp v24, v24, v24 quad_perm:[2,3,0,1] row_mask:0xf bank_mask:0xf bound_ctrl:1
	s_waitcnt lgkmcnt(3)
	v_pk_mul_f32 v[28:29], v[40:41], v[26:27] op_sel_hi:[1,0]
	v_add_f32_e32 v56, v56, v57
	v_add_f32_dpp v24, v24, v24 row_half_mirror row_mask:0xf bank_mask:0xf bound_ctrl:1
	v_pk_fma_f32 v[8:9], v[114:115], v[8:9], v[28:29]
	v_add_f32_dpp v56, v56, v56 quad_perm:[1,0,3,2] row_mask:0xf bank_mask:0xf bound_ctrl:1
	v_pk_fma_f32 v[114:115], v[24:25], v[32:33], v[8:9] op_sel_hi:[0,1,1]
	v_pk_mul_f32 v[8:9], v[42:43], v[26:27] op_sel_hi:[1,0]
	v_add_f32_dpp v56, v56, v56 quad_perm:[2,3,0,1] row_mask:0xf bank_mask:0xf bound_ctrl:1
	v_pk_fma_f32 v[8:9], v[116:117], v[10:11], v[8:9]
	v_add_u32_e32 v122, 0x600, v150
	v_add_f32_dpp v56, v56, v56 row_half_mirror row_mask:0xf bank_mask:0xf bound_ctrl:1
	v_pk_fma_f32 v[116:117], v[24:25], v[34:35], v[8:9] op_sel_hi:[0,1,1]
	s_waitcnt lgkmcnt(2)
	v_pk_mul_f32 v[8:9], v[44:45], v[26:27] op_sel_hi:[1,0]
	ds_write_b32 v151, v56 offset:1664
	v_pk_fma_f32 v[8:9], v[76:77], v[12:13], v[8:9]
	ds_read_b128 v[56:59], v149 offset:19200
	ds_read_b128 v[60:63], v149 offset:19216
	ds_read_b128 v[64:67], v149 offset:19456
	ds_read_b128 v[68:71], v149 offset:19472
	ds_read_b128 v[72:75], v149 offset:19712
	ds_read_b128 v[78:81], v149 offset:19728
	ds_read_b128 v[82:85], v149 offset:19968
	ds_read_b128 v[106:109], v149 offset:19984
	ds_read_b128 v[110:113], v149 offset:20224
	ds_read_b128 v[118:121], v149 offset:20240
	v_pk_fma_f32 v[76:77], v[24:25], v[36:37], v[8:9] op_sel_hi:[0,1,1]
	v_pk_mul_f32 v[8:9], v[46:47], v[26:27] op_sel_hi:[1,0]
	s_waitcnt lgkmcnt(7)
	v_pk_mul_f32 v[64:65], v[64:65], v[114:115]
	v_pk_fma_f32 v[8:9], v[86:87], v[14:15], v[8:9]
	ds_read2_b32 v[122:123], v122 offset0:96 offset1:128
	v_pk_fma_f32 v[86:87], v[24:25], v[38:39], v[8:9] op_sel_hi:[0,1,1]
	v_pk_mul_f32 v[8:9], v[48:49], v[114:115]
	v_pk_fma_f32 v[64:65], v[116:117], v[66:67], v[64:65]
	v_pk_fma_f32 v[8:9], v[116:117], v[50:51], v[8:9]
	s_waitcnt lgkmcnt(7)
; DI float red8(float x) { x += dppf(x, 0); x += dppf(x, 1); x += dppf(x, 2); return x; }
; DI void scan_item(const Params& p, int L, int c, int item, char* smem, bool dry) {
;     ...
;   auto prep4 = [&](float* PA, float* BON) {
;     float lw[8], la[8];
;     {
;       float4 t0 = *(const float4*)(LO + (0 * 32 + tt) * 64 + cs * 8), t1 = *(const float4*)(LO + (0 * 32 + tt) * 64 + cs * 8 + 4);
;       lw[0] = t0.x; lw[1] = t0.y; lw[2] = t0.z; lw[3] = t0.w; lw[4] = t1.x; lw[5] = t1.y; lw[6] = t1.z; lw[7] = t1.w;
;     ...
;   auto steps8 = [&](const float* PA, const float* Vst, float* Yst, int t0) {
; #pragma unroll
;     for (int t8 = 0; t8 < 8; ++t8) {
;       const int t = t0 + t8;
;       const float* pa = PA + (t + 1) * 320 + ks * 8;
;       const float4 xd0 = *(const float4*)(pa), xd1 = *(const float4*)(pa + 4);
;       const float4 xn0 = *(const float4*)(pa + 64), xn1 = *(const float4*)(pa + 68);
;       const float4 xb0 = *(const float4*)(pa + 128), xb1 = *(const float4*)(pa + 132);
;       const float4 xk0 = *(const float4*)(pa + 192), xk1 = *(const float4*)(pa + 196);
;       const float4 xr0 = *(const float4*)(pa + 256), xr1 = *(const float4*)(pa + 260);
;       const float xvv = Vst[(t + 1) * 32 + row32];
;       float sa0 = S[0] * n0.x, sa1 = S[1] * n0.y;
;       sa0 = fmaf(S[2], n0.z, sa0); sa1 = fmaf(S[3], n0.w, sa1);
;       sa0 = fmaf(S[4], n1.x, sa0); sa1 = fmaf(S[5], n1.y, sa1);
;       sa0 = fmaf(S[6], n1.z, sa0); sa1 = fmaf(S[7], n1.w, sa1);
;       float sa = red8(sa0 + sa1);
;       S[0] = fmaf(sa, b0.x, fmaf(S[0], d0.x, vv * k0.x)); S[1] = fmaf(sa, b0.y, fmaf(S[1], d0.y, vv * k0.y));
;       S[2] = fmaf(sa, b0.z, fmaf(S[2], d0.z, vv * k0.z)); S[3] = fmaf(sa, b0.w, fmaf(S[3], d0.w, vv * k0.w));
;       S[4] = fmaf(sa, b1.x, fmaf(S[4], d1.x, vv * k1.x)); S[5] = fmaf(sa, b1.y, fmaf(S[5], d1.y, vv * k1.y));
;       S[6] = fmaf(sa, b1.z, fmaf(S[6], d1.z, vv * k1.z)); S[7] = fmaf(sa, b1.w, fmaf(S[7], d1.w, vv * k1.w));
;       float y0 = S[0] * r0.x, y1 = S[1] * r0.y;
;       y0 = fmaf(S[2], r0.z, y0); y1 = fmaf(S[3], r0.w, y1);
;       y0 = fmaf(S[4], r1.x, y0); y1 = fmaf(S[5], r1.y, y1);
;       y0 = fmaf(S[6], r1.z, y0); y1 = fmaf(S[7], r1.w, y1);
;       float y = red8(y0 + y1);
;       Yst[t * 32 + row32] = y;
;       d0 = xd0; d1 = xd1; n0 = xn0; n1 = xn1; b0 = xb0; b1 = xb1; k0 = xk0; k1 = xk1; r0 = xr0; r1 = xr1; vv = xvv;
;     }
	v_pk_fma_f32 v[64:65], v[76:77], v[68:69], v[64:65]
	v_pk_fma_f32 v[8:9], v[76:77], v[52:53], v[8:9]
	v_pk_fma_f32 v[64:65], v[86:87], v[70:71], v[64:65]
	v_pk_fma_f32 v[8:9], v[86:87], v[54:55], v[8:9]
	v_add_f32_e32 v64, v65, v64
	v_add_f32_e32 v8, v8, v9
	s_waitcnt lgkmcnt(0)
	v_pk_mul_f32 v[66:67], v[82:83], v[122:123] op_sel_hi:[1,0]
	v_add_f32_dpp v64, v64, v64 quad_perm:[1,0,3,2] row_mask:0xf bank_mask:0xf bound_ctrl:1
	v_add_f32_dpp v8, v8, v8 quad_perm:[1,0,3,2] row_mask:0xf bank_mask:0xf bound_ctrl:1
	v_pk_fma_f32 v[56:57], v[114:115], v[56:57], v[66:67]
	v_add_f32_dpp v64, v64, v64 quad_perm:[2,3,0,1] row_mask:0xf bank_mask:0xf bound_ctrl:1
	v_add_f32_dpp v8, v8, v8 quad_perm:[2,3,0,1] row_mask:0xf bank_mask:0xf bound_ctrl:1
	v_pk_mul_f32 v[66:67], v[84:85], v[122:123] op_sel_hi:[1,0]
	v_add_f32_dpp v64, v64, v64 row_half_mirror row_mask:0xf bank_mask:0xf bound_ctrl:1
	v_add_f32_dpp v8, v8, v8 row_half_mirror row_mask:0xf bank_mask:0xf bound_ctrl:1
	v_pk_fma_f32 v[72:73], v[64:65], v[72:73], v[56:57] op_sel_hi:[0,1,1]
	ds_write_b32 v151, v8 offset:1792
	v_pk_fma_f32 v[58:59], v[116:117], v[58:59], v[66:67]
	v_mul_f32_e32 v65, v111, v73
	ds_read_b128 v[40:43], v149 offset:20480
	ds_read_b128 v[44:47], v149 offset:20496
	ds_read_b128 v[36:39], v149 offset:20736
	ds_read_b128 v[32:35], v149 offset:20752
	ds_read_b128 v[28:31], v149 offset:20992
	ds_read_b128 v[24:27], v149 offset:21008
	ds_read_b128 v[48:51], v149 offset:21248
	ds_read_b128 v[52:55], v149 offset:21264
	ds_read_b128 v[12:15], v149 offset:21504
	ds_read_b128 v[8:11], v149 offset:21520
	v_pk_mul_f32 v[66:67], v[106:107], v[122:123] op_sel_hi:[1,0]
	v_pk_fma_f32 v[74:75], v[64:65], v[74:75], v[58:59] op_sel_hi:[0,1,1]
	v_pk_fma_f32 v[60:61], v[76:77], v[60:61], v[66:67]
	v_mul_f32_e32 v57, v110, v72
	v_mov_b32_e32 v56, v123
	v_fmac_f32_e32 v65, v75, v113
	v_pk_mul_f32 v[66:67], v[108:109], v[122:123] op_sel_hi:[1,0]
	s_waitcnt lgkmcnt(3)
	v_pk_mul_f32 v[48:49], v[48:49], v[56:57] op_sel_hi:[1,0]
	v_pk_fma_f32 v[78:79], v[64:65], v[78:79], v[60:61] op_sel_hi:[0,1,1]
	v_pk_fma_f32 v[62:63], v[86:87], v[62:63], v[66:67]
	v_pk_fma_f32 v[68:69], v[72:73], v[40:41], v[48:49]
	v_pk_mul_f32 v[40:41], v[50:51], v[56:57] op_sel_hi:[1,0]
	v_fmac_f32_e32 v57, v74, v112
	v_fmac_f32_e32 v65, v79, v119
	v_pk_fma_f32 v[70:71], v[74:75], v[42:43], v[40:41]
	s_waitcnt lgkmcnt(2)
	v_pk_mul_f32 v[40:41], v[52:53], v[56:57] op_sel_hi:[1,0]
	v_fmac_f32_e32 v57, v78, v118
	v_pk_fma_f32 v[82:83], v[64:65], v[80:81], v[62:63] op_sel_hi:[0,1,1]
	v_pk_fma_f32 v[76:77], v[78:79], v[44:45], v[40:41]
	v_pk_mul_f32 v[40:41], v[54:55], v[56:57] op_sel_hi:[1,0]
	v_fmac_f32_e32 v57, v82, v120
	v_fmac_f32_e32 v65, v83, v121
	v_pk_fma_f32 v[80:81], v[82:83], v[46:47], v[40:41]
	v_add_f32_e32 v40, v57, v65
	v_pk_mul_f32 v[36:37], v[36:37], v[72:73]
	v_lshl_add_u32 v116, s34, 7, v147
	v_add_f32_dpp v40, v40, v40 quad_perm:[1,0,3,2] row_mask:0xf bank_mask:0xf bound_ctrl:1
	v_pk_fma_f32 v[36:37], v[74:75], v[38:39], v[36:37]
	s_nop 0
	v_add_f32_dpp v40, v40, v40 quad_perm:[2,3,0,1] row_mask:0xf bank_mask:0xf bound_ctrl:1
	v_pk_fma_f32 v[32:33], v[78:79], v[32:33], v[36:37]
	s_nop 0
	v_add_f32_dpp v40, v40, v40 row_half_mirror row_mask:0xf bank_mask:0xf bound_ctrl:1
	ds_write_b32 v151, v40 offset:1920
	s_waitcnt lgkmcnt(0)
	s_barrier
	ds_read_b128 v[40:43], v145
	ds_read_b128 v[44:47], v145 offset:16
	ds_read_b128 v[60:63], v145 offset:8192
	ds_read_b128 v[52:55], v145 offset:8208
	v_accvgpr_read_b32 v64, a56
	v_accvgpr_read_b32 v65, a57
	v_accvgpr_read_b32 v66, a58
	v_accvgpr_read_b32 v67, a59
	v_accvgpr_read_b32 v56, a60
	v_accvgpr_read_b32 v57, a61
	v_accvgpr_read_b32 v58, a62
	v_accvgpr_read_b32 v59, a63
	v_accvgpr_read_b32 v108, a64
	v_accvgpr_read_b32 v109, a65
	v_accvgpr_read_b32 v110, a66
	v_accvgpr_read_b32 v111, a67
	v_accvgpr_read_b32 v84, a68
	v_accvgpr_read_b32 v85, a69
	v_accvgpr_read_b32 v86, a70
	v_accvgpr_read_b32 v87, a71
	v_accvgpr_read_b32 v118, a72
	v_accvgpr_read_b32 v119, a73
	v_accvgpr_read_b32 v120, a74
	v_accvgpr_read_b32 v121, a75
	s_waitcnt lgkmcnt(3)
	v_add_f32_e32 v40, v40, v64
	v_add_f32_e32 v41, v41, v65
	v_add_f32_e32 v42, v42, v66
	v_add_f32_e32 v43, v43, v67
	v_accvgpr_read_b32 v64, a76
	v_accvgpr_read_b32 v65, a77
	v_accvgpr_read_b32 v66, a78
	v_accvgpr_read_b32 v67, a79
	s_waitcnt lgkmcnt(2)
	v_add_f32_e32 v46, v46, v58
	v_pk_mul_f32 v[106:107], v[94:95], v[108:109]
	s_waitcnt lgkmcnt(1)
	v_add_f32_e32 v48, v60, v84
	v_pk_mul_f32 v[108:109], v[106:107], v[106:107]
	s_waitcnt lgkmcnt(0)
; DI float ex2(float x) { return __builtin_amdgcn_exp2f(x); }
; DI float fexp(float x) { return __builtin_amdgcn_exp2f(x * 1.4426950408889634f); }
; DI float frcp(float x) { return __builtin_amdgcn_rcpf(x); }
; DI float red8(float x) { x += dppf(x, 0); x += dppf(x, 1); x += dppf(x, 2); return x; }
; DI void scan_item(const Params& p, int L, int c, int item, char* smem, bool dry) {
;     ...
;     float dec[8], kk[8], av[8], kp[8];
;     float ssq = 0.f, bon = 0.f;
; #pragma unroll
;     for (int e = 0; e < 8; ++e) {
;       const int ch = cs * 8 + e;
;       const float sg = frcp(1.f + fexp(-(lw[e] + PRM[4 * 64 + ch])));
;       dec[e] = ex2(-0.8750340f * sg);
;       float a = frcp(1.f + fexp(-(la[e] + PRM[5 * 64 + ch])));
;       av[e] = a;
;       kk[e] = km[e] * PRM[6 * 64 + ch];
;       ssq += kk[e] * kk[e];
;       kp[e] = km[e] * (1.f + (a - 1.f) * PRM[7 * 64 + ch]);
;       bon += rm[e] * kp[e] * PRM[8 * 64 + ch];
;     }
;     ssq = red8(ssq); bon = red8(bon);
;     const float inv = fminf(__builtin_amdgcn_rsqf(ssq), 1e12f);
;     float nk[8], bb[8];
; #pragma unroll
;     for (int e = 0; e < 8; ++e) { float kn = kk[e] * inv; nk[e] = -kn; bb[e] = kn * av[e]; }
	v_add_f32_e32 v54, v54, v66
	v_mul_f32_e32 v54, 0xbfb8aa3b, v54
	v_exp_f32_e32 v54, v54
	v_add_f32_e32 v60, v61, v85
	v_pk_mul_f32 v[110:111], v[92:93], v[110:111]
	v_mul_f32_e32 v60, 0xbfb8aa3b, v60
	v_add_f32_e32 v54, 1.0, v54
	v_rcp_f32_e32 v58, v54
	v_add_f32_e32 v54, v55, v67
	v_mul_f32_e32 v54, 0xbfb8aa3b, v54
	v_exp_f32_e32 v54, v54
	v_pk_mul_f32 v[112:113], v[110:111], v[110:111]
	v_add_f32_e32 v52, v52, v64
	v_add_f32_e32 v64, v108, v109
	v_exp_f32_e32 v60, v60
	v_pk_mul_f32 v[114:115], v[90:91], v[118:119]
	v_add_f32_e32 v64, v64, v112
	v_add_f32_e32 v44, v44, v56
	v_add_f32_e32 v45, v45, v57
	v_pk_mul_f32 v[56:57], v[114:115], v[114:115]
	v_add_f32_e32 v64, v64, v113
	v_pk_mul_f32 v[118:119], v[88:89], v[120:121]
	v_add_f32_e32 v54, 1.0, v54
	v_add_f32_e32 v56, v64, v56
	v_add_f32_e32 v47, v47, v59
	v_rcp_f32_e32 v59, v54
	v_pk_mul_f32 v[54:55], v[118:119], v[118:119]
	v_add_f32_e32 v56, v56, v57
	v_add_f32_e32 v60, 1.0, v60
	v_add_f32_e32 v54, v56, v54
	v_rcp_f32_e32 v85, v60
	v_add_f32_e32 v60, v62, v86
	v_add_f32_e32 v54, v54, v55
	v_mul_f32_e32 v60, 0xbfb8aa3b, v60
	v_exp_f32_e32 v60, v60
	v_add_f32_dpp v54, v54, v54 quad_perm:[1,0,3,2] row_mask:0xf bank_mask:0xf bound_ctrl:1
	v_mul_f32_e32 v48, 0xbfb8aa3b, v48
	v_exp_f32_e32 v48, v48
	v_add_f32_dpp v54, v54, v54 quad_perm:[2,3,0,1] row_mask:0xf bank_mask:0xf bound_ctrl:1
	v_add_f32_e32 v60, 1.0, v60
	v_rcp_f32_e32 v86, v60
	v_add_f32_dpp v54, v54, v54 row_half_mirror row_mask:0xf bank_mask:0xf bound_ctrl:1
	v_rsq_f32_e32 v54, v54
	v_add_f32_e32 v60, v63, v87
	v_add_f32_e32 v48, 1.0, v48
	v_mul_f32_e32 v60, 0xbfb8aa3b, v60
	v_min_f32_e32 v66, 0x5368d4a5, v54
	v_rcp_f32_e32 v84, v48
	v_exp_f32_e32 v60, v60
	v_pk_mul_f32 v[112:113], v[118:119], v[66:67] op_sel_hi:[1,0]
	v_accvgpr_read_b32 v118, a80
	v_accvgpr_read_b32 v119, a81
	v_accvgpr_read_b32 v120, a82
	v_accvgpr_read_b32 v121, a83
	v_accvgpr_read_b32 v48, a84
	v_accvgpr_read_b32 v49, a85
	v_accvgpr_read_b32 v50, a86
	v_accvgpr_read_b32 v51, a87
	v_pk_mul_f32 v[106:107], v[106:107], v[66:67] op_sel_hi:[1,0]
	v_add_f32_e32 v60, 1.0, v60
	v_xor_b32_e32 v55, 0x80000000, v107
	v_xor_b32_e32 v54, 0x80000000, v106
	v_pk_mul_f32 v[106:107], v[84:85], v[106:107]
	v_pk_add_f32 v[84:85], v[84:85], -1.0 op_sel_hi:[1,0]
	v_rcp_f32_e32 v87, v60
	v_pk_fma_f32 v[84:85], v[118:119], v[84:85], 1.0 op_sel_hi:[1,1,0]
	v_add_f32_e32 v53, v53, v65
	v_pk_mul_f32 v[84:85], v[94:95], v[84:85]
	v_mul_f32_e32 v52, 0xbfb8aa3b, v52
	v_pk_mul_f32 v[94:95], v[20:21], v[84:85]
	v_mul_f32_e32 v53, 0xbfb8aa3b, v53
	v_fma_f32 v94, v48, v94, 0
	v_exp_f32_e32 v52, v52
	v_exp_f32_e32 v53, v53
	v_fmac_f32_e32 v94, v49, v95
	v_pk_add_f32 v[48:49], v[86:87], -1.0 op_sel_hi:[1,0]
	v_pk_mul_f32 v[108:109], v[110:111], v[66:67] op_sel_hi:[1,0]
	v_pk_fma_f32 v[48:49], v[120:121], v[48:49], 1.0 op_sel_hi:[1,1,0]
	v_xor_b32_e32 v57, 0x80000000, v109
	v_xor_b32_e32 v56, 0x80000000, v108
	v_pk_mul_f32 v[108:109], v[86:87], v[108:109]
	v_pk_mul_f32 v[86:87], v[92:93], v[48:49]
	v_add_f32_e32 v52, 1.0, v52
	v_pk_mul_f32 v[48:49], v[22:23], v[86:87]
	v_add_f32_e32 v53, 1.0, v53
	v_fmac_f32_e32 v94, v50, v48
	v_rcp_f32_e32 v52, v52
	v_rcp_f32_e32 v53, v53
	v_fmac_f32_e32 v94, v51, v49
	v_accvgpr_read_b32 v48, a88
	v_accvgpr_read_b32 v49, a89
	v_accvgpr_read_b32 v50, a90
	v_accvgpr_read_b32 v51, a91
	v_mul_f32_e32 v40, 0xbfb8aa3b, v40
	v_mul_f32_e32 v41, 0xbfb8aa3b, v41
	v_mul_f32_e32 v42, 0xbfb8aa3b, v42
	v_mul_f32_e32 v43, 0xbfb8aa3b, v43
	v_exp_f32_e32 v40, v40
	v_exp_f32_e32 v41, v41
	v_exp_f32_e32 v42, v42
	v_exp_f32_e32 v43, v43
	v_mul_f32_e32 v44, 0xbfb8aa3b, v44
	v_accvgpr_read_b32 v60, a92
	v_accvgpr_read_b32 v61, a93
	v_accvgpr_read_b32 v62, a94
	v_accvgpr_read_b32 v63, a95
	v_mul_f32_e32 v45, 0xbfb8aa3b, v45
	v_mul_f32_e32 v46, 0xbfb8aa3b, v46
	v_mul_f32_e32 v47, 0xbfb8aa3b, v47
	v_pk_mul_f32 v[110:111], v[114:115], v[66:67] op_sel_hi:[1,0]
	v_exp_f32_e32 v44, v44
	v_exp_f32_e32 v45, v45
	v_exp_f32_e32 v46, v46
	v_exp_f32_e32 v47, v47
	v_xor_b32_e32 v65, 0x80000000, v111
	v_xor_b32_e32 v64, 0x80000000, v110
	v_pk_mul_f32 v[110:111], v[52:53], v[110:111]
	v_pk_add_f32 v[52:53], v[52:53], -1.0 op_sel_hi:[1,0]
	v_add_f32_e32 v40, 1.0, v40
	v_pk_fma_f32 v[48:49], v[48:49], v[52:53], 1.0 op_sel_hi:[1,1,0]
	v_add_f32_e32 v41, 1.0, v41
	v_pk_mul_f32 v[48:49], v[90:91], v[48:49]
	v_add_f32_e32 v42, 1.0, v42
	v_add_f32_e32 v43, 1.0, v43
	v_pk_mul_f32 v[52:53], v[16:17], v[48:49]
	v_rcp_f32_e32 v40, v40
	v_rcp_f32_e32 v41, v41
	v_rcp_f32_e32 v42, v42
	v_rcp_f32_e32 v43, v43
	v_add_f32_e32 v44, 1.0, v44
	v_add_f32_e32 v45, 1.0, v45
	v_add_f32_e32 v46, 1.0, v46
	v_add_f32_e32 v47, 1.0, v47
	v_fmac_f32_e32 v94, v60, v52
	v_rcp_f32_e32 v44, v44
	v_rcp_f32_e32 v45, v45
	v_rcp_f32_e32 v46, v46
	v_rcp_f32_e32 v47, v47
	v_fmac_f32_e32 v94, v61, v53
	v_pk_add_f32 v[52:53], v[58:59], -1.0 op_sel_hi:[1,0]
	v_mul_f32_e32 v40, 0xbf60023a, v40
	v_pk_fma_f32 v[50:51], v[50:51], v[52:53], 1.0 op_sel_hi:[1,1,0]
	v_mul_f32_e32 v41, 0xbf60023a, v41
	v_pk_mul_f32 v[50:51], v[88:89], v[50:51]
	v_mul_f32_e32 v42, 0xbf60023a, v42
	v_mul_f32_e32 v43, 0xbf60023a, v43
	v_pk_mul_f32 v[52:53], v[18:19], v[50:51]
	v_exp_f32_e32 v40, v40
	v_exp_f32_e32 v41, v41
	v_exp_f32_e32 v42, v42
	v_exp_f32_e32 v43, v43
	v_mul_f32_e32 v44, 0xbf60023a, v44
	v_mul_f32_e32 v45, 0xbf60023a, v45
	v_mul_f32_e32 v46, 0xbf60023a, v46
	v_mul_f32_e32 v47, 0xbf60023a, v47
	v_fmac_f32_e32 v94, v62, v52
	v_pk_fma_f32 v[32:33], v[82:83], v[34:35], v[32:33]
	v_exp_f32_e32 v44, v44
	v_exp_f32_e32 v45, v45
	v_exp_f32_e32 v46, v46
	v_exp_f32_e32 v47, v47
	v_fmac_f32_e32 v94, v63, v53
	v_add_f32_e32 v32, v32, v33
; DI void scan_item(const Params& p, int L, int c, int item, char* smem, bool dry) {
;     ...
;     for (int e = 0; e < 8; ++e) { float kn = kk[e] * inv; nk[e] = -kn; bb[e] = kn * av[e]; }
;     float* pa = PA + tt * 320 + cs * 8;
;     *(float4*)(pa) = make_float4(dec[0], dec[1], dec[2], dec[3]); *(float4*)(pa + 4) = make_float4(dec[4], dec[5], dec[6], dec[7]);
;     *(float4*)(pa + 64) = make_float4(nk[0], nk[1], nk[2], nk[3]); *(float4*)(pa + 68) = make_float4(nk[4], nk[5], nk[6], nk[7]);
;     *(float4*)(pa + 128) = make_float4(bb[0], bb[1], bb[2], bb[3]); *(float4*)(pa + 132) = make_float4(bb[4], bb[5], bb[6], bb[7]);
;     *(float4*)(pa + 192) = make_float4(kp[0], kp[1], kp[2], kp[3]); *(float4*)(pa + 196) = make_float4(kp[4], kp[5], kp[6], kp[7]);
;     *(float4*)(pa + 256) = make_float4(rm[0], rm[1], rm[2], rm[3]); *(float4*)(pa + 260) = make_float4(rm[4], rm[5], rm[6], rm[7]);
;     BON[tt] = bon;
;     ...
;   auto steps8 = [&](const float* PA, const float* Vst, float* Yst, int t0) {
; #pragma unroll
;     for (int t8 = 0; t8 < 8; ++t8) {
;       const int t = t0 + t8;
;       const float* pa = PA + (t + 1) * 320 + ks * 8;
;       const float4 xd0 = *(const float4*)(pa), xd1 = *(const float4*)(pa + 4);
;       const float4 xn0 = *(const float4*)(pa + 64), xn1 = *(const float4*)(pa + 68);
;       const float4 xb0 = *(const float4*)(pa + 128), xb1 = *(const float4*)(pa + 132);
;       const float4 xk0 = *(const float4*)(pa + 192), xk1 = *(const float4*)(pa + 196);
;       const float4 xr0 = *(const float4*)(pa + 256), xr1 = *(const float4*)(pa + 260);
;       const float xvv = Vst[(t + 1) * 32 + row32];
;       float sa0 = S[0] * n0.x, sa1 = S[1] * n0.y;
;       sa0 = fmaf(S[2], n0.z, sa0); sa1 = fmaf(S[3], n0.w, sa1);
;       sa0 = fmaf(S[4], n1.x, sa0); sa1 = fmaf(S[5], n1.y, sa1);
;       sa0 = fmaf(S[6], n1.z, sa0); sa1 = fmaf(S[7], n1.w, sa1);
;       float sa = red8(sa0 + sa1);
;       S[0] = fmaf(sa, b0.x, fmaf(S[0], d0.x, vv * k0.x)); S[1] = fmaf(sa, b0.y, fmaf(S[1], d0.y, vv * k0.y));
;       S[2] = fmaf(sa, b0.z, fmaf(S[2], d0.z, vv * k0.z)); S[3] = fmaf(sa, b0.w, fmaf(S[3], d0.w, vv * k0.w));
;       S[4] = fmaf(sa, b1.x, fmaf(S[4], d1.x, vv * k1.x)); S[5] = fmaf(sa, b1.y, fmaf(S[5], d1.y, vv * k1.y));
;       S[6] = fmaf(sa, b1.z, fmaf(S[6], d1.z, vv * k1.z)); S[7] = fmaf(sa, b1.w, fmaf(S[7], d1.w, vv * k1.w));
	v_xor_b32_e32 v67, 0x80000000, v113
	v_add_f32_dpp v52, v94, v94 quad_perm:[1,0,3,2] row_mask:0xf bank_mask:0xf bound_ctrl:1
	v_add_f32_dpp v32, v32, v32 quad_perm:[1,0,3,2] row_mask:0xf bank_mask:0xf bound_ctrl:1
	v_xor_b32_e32 v66, 0x80000000, v112
	v_add_f32_dpp v52, v52, v52 quad_perm:[2,3,0,1] row_mask:0xf bank_mask:0xf bound_ctrl:1
	v_add_f32_dpp v32, v32, v32 quad_perm:[2,3,0,1] row_mask:0xf bank_mask:0xf bound_ctrl:1
	v_pk_mul_f32 v[112:113], v[58:59], v[112:113]
	v_add_f32_dpp v52, v52, v52 row_half_mirror row_mask:0xf bank_mask:0xf bound_ctrl:1
	ds_write_b128 v153, v[40:43]
	ds_write_b128 v153, v[44:47] offset:16
	ds_write_b128 v153, v[54:57] offset:256
	ds_write_b128 v153, v[64:67] offset:272
	ds_write_b128 v153, v[106:109] offset:512
	ds_write_b128 v153, v[110:113] offset:528
	ds_write_b128 v153, v[84:87] offset:768
	ds_write_b128 v153, v[48:51] offset:784
	ds_write_b128 v153, v[20:23] offset:1024
	ds_write_b128 v153, v[16:19] offset:1040
	ds_write_b32 v116, v52
	v_add_f32_dpp v32, v32, v32 row_half_mirror row_mask:0xf bank_mask:0xf bound_ctrl:1
	ds_read_b128 v[16:19], v149 offset:21760
	ds_read_b128 v[20:23], v149 offset:21776
	ds_read_b128 v[40:43], v149 offset:22016
	ds_read_b128 v[44:47], v149 offset:22032
	ds_read_b128 v[48:51], v149 offset:22272
	ds_read_b128 v[52:55], v149 offset:22288
	ds_read_b128 v[56:59], v149 offset:22528
	ds_read_b128 v[60:63], v149 offset:22544
	ds_read_b128 v[64:67], v149 offset:22784
	ds_read_b128 v[84:87], v149 offset:22800
	v_pk_fma_f32 v[90:91], v[32:33], v[28:29], v[68:69] op_sel_hi:[0,1,1]
	v_add_u32_e32 v110, 0x800, v150
	v_pk_fma_f32 v[92:93], v[32:33], v[30:31], v[70:71] op_sel_hi:[0,1,1]
	s_waitcnt lgkmcnt(7)
	v_pk_mul_f32 v[40:41], v[40:41], v[90:91]
	ds_read2_b32 v[88:89], v110 offset0:32 offset1:64
	v_pk_fma_f32 v[94:95], v[32:33], v[24:25], v[76:77] op_sel_hi:[0,1,1]
	v_pk_fma_f32 v[40:41], v[92:93], v[42:43], v[40:41]
	v_pk_fma_f32 v[106:107], v[32:33], v[26:27], v[80:81] op_sel_hi:[0,1,1]
	v_pk_mul_f32 v[12:13], v[12:13], v[90:91]
	s_waitcnt lgkmcnt(7)
	v_pk_fma_f32 v[40:41], v[94:95], v[44:45], v[40:41]
	v_pk_fma_f32 v[12:13], v[92:93], v[14:15], v[12:13]
	v_pk_fma_f32 v[40:41], v[106:107], v[46:47], v[40:41]
	v_pk_fma_f32 v[12:13], v[94:95], v[8:9], v[12:13]
	v_add_f32_e32 v40, v41, v40
	v_pk_fma_f32 v[12:13], v[106:107], v[10:11], v[12:13]
	s_nop 0
	v_add_f32_dpp v40, v40, v40 quad_perm:[1,0,3,2] row_mask:0xf bank_mask:0xf bound_ctrl:1
	v_add_f32_e32 v8, v12, v13
	s_waitcnt lgkmcnt(0)
	v_pk_mul_f32 v[42:43], v[56:57], v[88:89] op_sel_hi:[1,0]
	v_add_f32_dpp v40, v40, v40 quad_perm:[2,3,0,1] row_mask:0xf bank_mask:0xf bound_ctrl:1
	v_add_f32_dpp v8, v8, v8 quad_perm:[1,0,3,2] row_mask:0xf bank_mask:0xf bound_ctrl:1
	v_pk_fma_f32 v[16:17], v[90:91], v[16:17], v[42:43]
	v_add_f32_dpp v40, v40, v40 row_half_mirror row_mask:0xf bank_mask:0xf bound_ctrl:1
	v_add_f32_dpp v8, v8, v8 quad_perm:[2,3,0,1] row_mask:0xf bank_mask:0xf bound_ctrl:1
	v_pk_fma_f32 v[90:91], v[40:41], v[48:49], v[16:17] op_sel_hi:[0,1,1]
	v_pk_mul_f32 v[16:17], v[58:59], v[88:89] op_sel_hi:[1,0]
	v_add_f32_dpp v8, v8, v8 row_half_mirror row_mask:0xf bank_mask:0xf bound_ctrl:1
	v_pk_fma_f32 v[16:17], v[92:93], v[18:19], v[16:17]
	ds_write_b32 v151, v8 offset:2048
	v_pk_fma_f32 v[92:93], v[40:41], v[50:51], v[16:17] op_sel_hi:[0,1,1]
	v_pk_mul_f32 v[16:17], v[60:61], v[88:89] op_sel_hi:[1,0]
	ds_read_b128 v[8:11], v149 offset:23040
	ds_read_b128 v[12:15], v149 offset:23056
	ds_read_b128 v[24:27], v149 offset:23296
	ds_read_b128 v[28:31], v149 offset:23312
	ds_read_b128 v[32:35], v149 offset:23552
	ds_read_b128 v[36:39], v149 offset:23568
	ds_read_b128 v[68:71], v149 offset:23808
	ds_read_b128 v[72:75], v149 offset:23824
	ds_read_b128 v[76:79], v149 offset:24064
	ds_read_b128 v[80:83], v149 offset:24080
	v_pk_fma_f32 v[16:17], v[94:95], v[20:21], v[16:17]
	s_waitcnt lgkmcnt(7)
	v_pk_mul_f32 v[24:25], v[24:25], v[90:91]
	v_pk_fma_f32 v[94:95], v[40:41], v[52:53], v[16:17] op_sel_hi:[0,1,1]
	v_pk_mul_f32 v[16:17], v[62:63], v[88:89] op_sel_hi:[1,0]
	v_pk_fma_f32 v[24:25], v[92:93], v[26:27], v[24:25]
	v_pk_fma_f32 v[16:17], v[106:107], v[22:23], v[16:17]
	s_waitcnt lgkmcnt(6)
	v_pk_fma_f32 v[24:25], v[94:95], v[28:29], v[24:25]
	v_pk_fma_f32 v[106:107], v[40:41], v[54:55], v[16:17] op_sel_hi:[0,1,1]
	v_pk_mul_f32 v[16:17], v[64:65], v[90:91]
	v_pk_fma_f32 v[16:17], v[92:93], v[66:67], v[16:17]
	v_pk_fma_f32 v[24:25], v[106:107], v[30:31], v[24:25]
	v_pk_fma_f32 v[16:17], v[94:95], v[84:85], v[16:17]
	v_add_f32_e32 v24, v25, v24
	v_pk_fma_f32 v[16:17], v[106:107], v[86:87], v[16:17]
	s_nop 0
	v_add_f32_dpp v24, v24, v24 quad_perm:[1,0,3,2] row_mask:0xf bank_mask:0xf bound_ctrl:1
	v_mov_b32_e32 v26, v89
	v_add_f32_e32 v16, v16, v17
	v_add_f32_dpp v24, v24, v24 quad_perm:[2,3,0,1] row_mask:0xf bank_mask:0xf bound_ctrl:1
	s_waitcnt lgkmcnt(3)
	v_pk_mul_f32 v[28:29], v[68:69], v[26:27] op_sel_hi:[1,0]
	v_add_f32_dpp v16, v16, v16 quad_perm:[1,0,3,2] row_mask:0xf bank_mask:0xf bound_ctrl:1
	v_add_f32_dpp v24, v24, v24 row_half_mirror row_mask:0xf bank_mask:0xf bound_ctrl:1
	v_pk_fma_f32 v[8:9], v[90:91], v[8:9], v[28:29]
	v_add_f32_dpp v16, v16, v16 quad_perm:[2,3,0,1] row_mask:0xf bank_mask:0xf bound_ctrl:1
	v_pk_fma_f32 v[88:89], v[24:25], v[32:33], v[8:9] op_sel_hi:[0,1,1]
	v_pk_mul_f32 v[8:9], v[70:71], v[26:27] op_sel_hi:[1,0]
	v_add_f32_dpp v16, v16, v16 row_half_mirror row_mask:0xf bank_mask:0xf bound_ctrl:1
	v_pk_fma_f32 v[8:9], v[92:93], v[10:11], v[8:9]
	ds_write_b32 v151, v16 offset:2176
	v_pk_fma_f32 v[90:91], v[24:25], v[34:35], v[8:9] op_sel_hi:[0,1,1]
	s_waitcnt lgkmcnt(3)
; DI float red8(float x) { x += dppf(x, 0); x += dppf(x, 1); x += dppf(x, 2); return x; }
; DI void scan_item(const Params& p, int L, int c, int item, char* smem, bool dry) {
;     ...
;   auto steps8 = [&](const float* PA, const float* Vst, float* Yst, int t0) {
; #pragma unroll
;     for (int t8 = 0; t8 < 8; ++t8) {
;       const int t = t0 + t8;
;       const float* pa = PA + (t + 1) * 320 + ks * 8;
;       const float4 xd0 = *(const float4*)(pa), xd1 = *(const float4*)(pa + 4);
;       const float4 xn0 = *(const float4*)(pa + 64), xn1 = *(const float4*)(pa + 68);
;       const float4 xb0 = *(const float4*)(pa + 128), xb1 = *(const float4*)(pa + 132);
;       const float4 xk0 = *(const float4*)(pa + 192), xk1 = *(const float4*)(pa + 196);
;       const float4 xr0 = *(const float4*)(pa + 256), xr1 = *(const float4*)(pa + 260);
;       const float xvv = Vst[(t + 1) * 32 + row32];
;       float sa0 = S[0] * n0.x, sa1 = S[1] * n0.y;
;       sa0 = fmaf(S[2], n0.z, sa0); sa1 = fmaf(S[3], n0.w, sa1);
;       sa0 = fmaf(S[4], n1.x, sa0); sa1 = fmaf(S[5], n1.y, sa1);
;       sa0 = fmaf(S[6], n1.z, sa0); sa1 = fmaf(S[7], n1.w, sa1);
;       float sa = red8(sa0 + sa1);
;       S[0] = fmaf(sa, b0.x, fmaf(S[0], d0.x, vv * k0.x)); S[1] = fmaf(sa, b0.y, fmaf(S[1], d0.y, vv * k0.y));
;       S[2] = fmaf(sa, b0.z, fmaf(S[2], d0.z, vv * k0.z)); S[3] = fmaf(sa, b0.w, fmaf(S[3], d0.w, vv * k0.w));
;       S[4] = fmaf(sa, b1.x, fmaf(S[4], d1.x, vv * k1.x)); S[5] = fmaf(sa, b1.y, fmaf(S[5], d1.y, vv * k1.y));
;       S[6] = fmaf(sa, b1.z, fmaf(S[6], d1.z, vv * k1.z)); S[7] = fmaf(sa, b1.w, fmaf(S[7], d1.w, vv * k1.w));
;       float y0 = S[0] * r0.x, y1 = S[1] * r0.y;
;       y0 = fmaf(S[2], r0.z, y0); y1 = fmaf(S[3], r0.w, y1);
;       y0 = fmaf(S[4], r1.x, y0); y1 = fmaf(S[5], r1.y, y1);
;       y0 = fmaf(S[6], r1.z, y0); y1 = fmaf(S[7], r1.w, y1);
;       float y = red8(y0 + y1);
;       Yst[t * 32 + row32] = y;
;       d0 = xd0; d1 = xd1; n0 = xn0; n1 = xn1; b0 = xb0; b1 = xb1; k0 = xk0; k1 = xk1; r0 = xr0; r1 = xr1; vv = xvv;
;     }
	v_pk_mul_f32 v[8:9], v[72:73], v[26:27] op_sel_hi:[1,0]
	ds_read_b128 v[16:19], v149 offset:24320
	ds_read_b128 v[20:23], v149 offset:24336
	ds_read_b128 v[40:43], v149 offset:24576
	ds_read_b128 v[44:47], v149 offset:24592
	ds_read_b128 v[48:51], v149 offset:24832
	ds_read_b128 v[52:55], v149 offset:24848
	ds_read_b128 v[56:59], v149 offset:25088
	ds_read_b128 v[60:63], v149 offset:25104
	ds_read_b128 v[64:67], v149 offset:25344
	ds_read_b128 v[84:87], v149 offset:25360
	ds_read2_b32 v[108:109], v110 offset0:96 offset1:128
	v_pk_fma_f32 v[8:9], v[94:95], v[12:13], v[8:9]
	s_waitcnt lgkmcnt(8)
	v_pk_mul_f32 v[40:41], v[40:41], v[88:89]
	v_pk_fma_f32 v[92:93], v[24:25], v[36:37], v[8:9] op_sel_hi:[0,1,1]
	v_pk_mul_f32 v[8:9], v[74:75], v[26:27] op_sel_hi:[1,0]
	v_pk_fma_f32 v[40:41], v[90:91], v[42:43], v[40:41]
	v_pk_fma_f32 v[8:9], v[106:107], v[14:15], v[8:9]
	s_waitcnt lgkmcnt(7)
	v_pk_fma_f32 v[40:41], v[92:93], v[44:45], v[40:41]
	v_pk_fma_f32 v[94:95], v[24:25], v[38:39], v[8:9] op_sel_hi:[0,1,1]
	v_pk_mul_f32 v[8:9], v[76:77], v[88:89]
	v_pk_fma_f32 v[8:9], v[90:91], v[78:79], v[8:9]
	v_pk_fma_f32 v[40:41], v[94:95], v[46:47], v[40:41]
	v_pk_fma_f32 v[8:9], v[92:93], v[80:81], v[8:9]
	v_add_f32_e32 v40, v41, v40
	v_pk_fma_f32 v[8:9], v[94:95], v[82:83], v[8:9]
	s_nop 0
	v_add_f32_dpp v40, v40, v40 quad_perm:[1,0,3,2] row_mask:0xf bank_mask:0xf bound_ctrl:1
	v_add_f32_e32 v8, v8, v9
	s_waitcnt lgkmcnt(0)
	v_pk_mul_f32 v[42:43], v[56:57], v[108:109] op_sel_hi:[1,0]
	v_add_f32_dpp v40, v40, v40 quad_perm:[2,3,0,1] row_mask:0xf bank_mask:0xf bound_ctrl:1
	v_add_f32_dpp v8, v8, v8 quad_perm:[1,0,3,2] row_mask:0xf bank_mask:0xf bound_ctrl:1
	v_pk_fma_f32 v[16:17], v[88:89], v[16:17], v[42:43]
	v_add_f32_dpp v40, v40, v40 row_half_mirror row_mask:0xf bank_mask:0xf bound_ctrl:1
	v_add_f32_dpp v8, v8, v8 quad_perm:[2,3,0,1] row_mask:0xf bank_mask:0xf bound_ctrl:1
	v_pk_fma_f32 v[88:89], v[40:41], v[48:49], v[16:17] op_sel_hi:[0,1,1]
	v_pk_mul_f32 v[16:17], v[58:59], v[108:109] op_sel_hi:[1,0]
	v_add_f32_dpp v8, v8, v8 row_half_mirror row_mask:0xf bank_mask:0xf bound_ctrl:1
	v_pk_fma_f32 v[16:17], v[90:91], v[18:19], v[16:17]
	ds_write_b32 v151, v8 offset:2304
	v_pk_fma_f32 v[90:91], v[40:41], v[50:51], v[16:17] op_sel_hi:[0,1,1]
	v_pk_mul_f32 v[16:17], v[60:61], v[108:109] op_sel_hi:[1,0]
	ds_read_b128 v[8:11], v149 offset:25600
	ds_read_b128 v[12:15], v149 offset:25616
	ds_read_b128 v[24:27], v149 offset:25856
	ds_read_b128 v[28:31], v149 offset:25872
	ds_read_b128 v[32:35], v149 offset:26112
	ds_read_b128 v[36:39], v149 offset:26128
	ds_read_b128 v[68:71], v149 offset:26368
	ds_read_b128 v[72:75], v149 offset:26384
	ds_read_b128 v[76:79], v149 offset:26624
	ds_read_b128 v[80:83], v149 offset:26640
	v_pk_fma_f32 v[16:17], v[92:93], v[20:21], v[16:17]
	s_waitcnt lgkmcnt(7)
	v_pk_mul_f32 v[24:25], v[24:25], v[88:89]
	v_pk_fma_f32 v[92:93], v[40:41], v[52:53], v[16:17] op_sel_hi:[0,1,1]
	v_pk_mul_f32 v[16:17], v[62:63], v[108:109] op_sel_hi:[1,0]
	v_pk_fma_f32 v[24:25], v[90:91], v[26:27], v[24:25]
	v_pk_fma_f32 v[16:17], v[94:95], v[22:23], v[16:17]
	s_waitcnt lgkmcnt(6)
	v_pk_fma_f32 v[24:25], v[92:93], v[28:29], v[24:25]
	v_pk_fma_f32 v[94:95], v[40:41], v[54:55], v[16:17] op_sel_hi:[0,1,1]
	v_pk_fma_f32 v[24:25], v[94:95], v[30:31], v[24:25]
	v_mov_b32_e32 v26, v109
	v_add_f32_e32 v24, v25, v24
	v_pk_mul_f32 v[16:17], v[64:65], v[88:89]
	s_nop 0
	v_add_f32_dpp v24, v24, v24 quad_perm:[1,0,3,2] row_mask:0xf bank_mask:0xf bound_ctrl:1
	s_waitcnt lgkmcnt(3)
	v_pk_mul_f32 v[28:29], v[68:69], v[26:27] op_sel_hi:[1,0]
	v_add_f32_dpp v24, v24, v24 quad_perm:[2,3,0,1] row_mask:0xf bank_mask:0xf bound_ctrl:1
	v_pk_fma_f32 v[16:17], v[90:91], v[66:67], v[16:17]
	v_pk_fma_f32 v[8:9], v[88:89], v[8:9], v[28:29]
	v_add_f32_dpp v24, v24, v24 row_half_mirror row_mask:0xf bank_mask:0xf bound_ctrl:1
	v_pk_fma_f32 v[16:17], v[92:93], v[84:85], v[16:17]
	v_pk_fma_f32 v[88:89], v[24:25], v[32:33], v[8:9] op_sel_hi:[0,1,1]
	v_pk_mul_f32 v[8:9], v[70:71], v[26:27] op_sel_hi:[1,0]
	v_pk_fma_f32 v[16:17], v[94:95], v[86:87], v[16:17]
	v_pk_fma_f32 v[8:9], v[90:91], v[10:11], v[8:9]
	v_add_f32_e32 v16, v16, v17
	v_pk_fma_f32 v[90:91], v[24:25], v[34:35], v[8:9] op_sel_hi:[0,1,1]
	s_waitcnt lgkmcnt(2)
	v_pk_mul_f32 v[8:9], v[72:73], v[26:27] op_sel_hi:[1,0]
	v_add_f32_dpp v16, v16, v16 quad_perm:[1,0,3,2] row_mask:0xf bank_mask:0xf bound_ctrl:1
	v_pk_fma_f32 v[8:9], v[92:93], v[12:13], v[8:9]
	s_nop 0
	v_add_f32_dpp v16, v16, v16 quad_perm:[2,3,0,1] row_mask:0xf bank_mask:0xf bound_ctrl:1
	v_pk_fma_f32 v[92:93], v[24:25], v[36:37], v[8:9] op_sel_hi:[0,1,1]
	v_pk_mul_f32 v[8:9], v[74:75], v[26:27] op_sel_hi:[1,0]
	v_add_f32_dpp v16, v16, v16 row_half_mirror row_mask:0xf bank_mask:0xf bound_ctrl:1
	v_pk_fma_f32 v[8:9], v[94:95], v[14:15], v[8:9]
	ds_write_b32 v151, v16 offset:2432
	v_pk_fma_f32 v[94:95], v[24:25], v[38:39], v[8:9] op_sel_hi:[0,1,1]
	s_waitcnt lgkmcnt(2)
	v_pk_mul_f32 v[8:9], v[76:77], v[88:89]
	ds_read_b128 v[16:19], v149 offset:26880
	ds_read_b128 v[20:23], v149 offset:26896
	ds_read_b128 v[40:43], v149 offset:27136
	ds_read_b128 v[44:47], v149 offset:27152
	ds_read_b128 v[48:51], v149 offset:27392
	ds_read_b128 v[52:55], v149 offset:27408
	ds_read_b128 v[56:59], v149 offset:27648
	ds_read_b128 v[60:63], v149 offset:27664
	ds_read_b128 v[64:67], v149 offset:27904
	ds_read_b128 v[84:87], v149 offset:27920
	ds_read2_b32 v[106:107], v110 offset0:160 offset1:192
	v_pk_fma_f32 v[8:9], v[90:91], v[78:79], v[8:9]
	s_waitcnt lgkmcnt(12)
	v_pk_fma_f32 v[8:9], v[92:93], v[80:81], v[8:9]
	s_waitcnt lgkmcnt(8)
; DI float red8(float x) { x += dppf(x, 0); x += dppf(x, 1); x += dppf(x, 2); return x; }
; DI void scan_item(const Params& p, int L, int c, int item, char* smem, bool dry) {
;     ...
;   auto steps8 = [&](const float* PA, const float* Vst, float* Yst, int t0) {
; #pragma unroll
;     for (int t8 = 0; t8 < 8; ++t8) {
;       const int t = t0 + t8;
;       const float* pa = PA + (t + 1) * 320 + ks * 8;
;       const float4 xd0 = *(const float4*)(pa), xd1 = *(const float4*)(pa + 4);
;       const float4 xn0 = *(const float4*)(pa + 64), xn1 = *(const float4*)(pa + 68);
;       const float4 xb0 = *(const float4*)(pa + 128), xb1 = *(const float4*)(pa + 132);
;       const float4 xk0 = *(const float4*)(pa + 192), xk1 = *(const float4*)(pa + 196);
;       const float4 xr0 = *(const float4*)(pa + 256), xr1 = *(const float4*)(pa + 260);
;       const float xvv = Vst[(t + 1) * 32 + row32];
;       float sa0 = S[0] * n0.x, sa1 = S[1] * n0.y;
;       sa0 = fmaf(S[2], n0.z, sa0); sa1 = fmaf(S[3], n0.w, sa1);
;       sa0 = fmaf(S[4], n1.x, sa0); sa1 = fmaf(S[5], n1.y, sa1);
;       sa0 = fmaf(S[6], n1.z, sa0); sa1 = fmaf(S[7], n1.w, sa1);
;       float sa = red8(sa0 + sa1);
;       S[0] = fmaf(sa, b0.x, fmaf(S[0], d0.x, vv * k0.x)); S[1] = fmaf(sa, b0.y, fmaf(S[1], d0.y, vv * k0.y));
;       S[2] = fmaf(sa, b0.z, fmaf(S[2], d0.z, vv * k0.z)); S[3] = fmaf(sa, b0.w, fmaf(S[3], d0.w, vv * k0.w));
;       S[4] = fmaf(sa, b1.x, fmaf(S[4], d1.x, vv * k1.x)); S[5] = fmaf(sa, b1.y, fmaf(S[5], d1.y, vv * k1.y));
;       S[6] = fmaf(sa, b1.z, fmaf(S[6], d1.z, vv * k1.z)); S[7] = fmaf(sa, b1.w, fmaf(S[7], d1.w, vv * k1.w));
;       float y0 = S[0] * r0.x, y1 = S[1] * r0.y;
;       y0 = fmaf(S[2], r0.z, y0); y1 = fmaf(S[3], r0.w, y1);
;       y0 = fmaf(S[4], r1.x, y0); y1 = fmaf(S[5], r1.y, y1);
;       y0 = fmaf(S[6], r1.z, y0); y1 = fmaf(S[7], r1.w, y1);
;       float y = red8(y0 + y1);
;       Yst[t * 32 + row32] = y;
;       d0 = xd0; d1 = xd1; n0 = xn0; n1 = xn1; b0 = xb0; b1 = xb1; k0 = xk0; k1 = xk1; r0 = xr0; r1 = xr1; vv = xvv;
;     }
	v_pk_mul_f32 v[40:41], v[40:41], v[88:89]
	v_pk_fma_f32 v[8:9], v[94:95], v[82:83], v[8:9]
	v_pk_fma_f32 v[40:41], v[90:91], v[42:43], v[40:41]
	v_add_f32_e32 v8, v8, v9
	s_waitcnt lgkmcnt(7)
	v_pk_fma_f32 v[40:41], v[92:93], v[44:45], v[40:41]
	s_waitcnt lgkmcnt(0)
	v_pk_mul_f32 v[42:43], v[56:57], v[106:107] op_sel_hi:[1,0]
	v_add_f32_dpp v8, v8, v8 quad_perm:[1,0,3,2] row_mask:0xf bank_mask:0xf bound_ctrl:1
	v_pk_fma_f32 v[40:41], v[94:95], v[46:47], v[40:41]
	v_pk_mul_f32 v[56:57], v[62:63], v[106:107] op_sel_hi:[1,0]
	v_add_f32_dpp v8, v8, v8 quad_perm:[2,3,0,1] row_mask:0xf bank_mask:0xf bound_ctrl:1
	v_add_f32_e32 v40, v41, v40
	v_pk_mul_f32 v[44:45], v[58:59], v[106:107] op_sel_hi:[1,0]
	v_add_f32_dpp v8, v8, v8 row_half_mirror row_mask:0xf bank_mask:0xf bound_ctrl:1
	v_add_f32_dpp v40, v40, v40 quad_perm:[1,0,3,2] row_mask:0xf bank_mask:0xf bound_ctrl:1
	ds_write_b32 v151, v8 offset:2560
	ds_read_b128 v[8:11], v149 offset:28160
	ds_read_b128 v[12:15], v149 offset:28176
	ds_read_b128 v[24:27], v149 offset:28416
	ds_read_b128 v[28:31], v149 offset:28432
	ds_read_b128 v[32:35], v149 offset:28672
	ds_read_b128 v[36:39], v149 offset:28688
	ds_read_b128 v[68:71], v149 offset:28928
	ds_read_b128 v[72:75], v149 offset:28944
	ds_read_b128 v[76:79], v149 offset:29184
	ds_read_b128 v[80:83], v149 offset:29200
	v_add_f32_dpp v40, v40, v40 quad_perm:[2,3,0,1] row_mask:0xf bank_mask:0xf bound_ctrl:1
	v_pk_fma_f32 v[22:23], v[94:95], v[22:23], v[56:57]
	v_pk_fma_f32 v[18:19], v[90:91], v[18:19], v[44:45]
	v_add_f32_dpp v40, v40, v40 row_half_mirror row_mask:0xf bank_mask:0xf bound_ctrl:1
	v_pk_fma_f32 v[56:57], v[40:41], v[54:55], v[22:23] op_sel_hi:[0,1,1]
	v_mov_b32_e32 v22, v107
	v_pk_fma_f32 v[16:17], v[88:89], v[16:17], v[42:43]
	v_pk_mul_f32 v[46:47], v[60:61], v[106:107] op_sel_hi:[1,0]
	v_pk_fma_f32 v[60:61], v[40:41], v[50:51], v[18:19] op_sel_hi:[0,1,1]
	s_waitcnt lgkmcnt(3)
	v_pk_mul_f32 v[18:19], v[70:71], v[22:23] op_sel_hi:[1,0]
	v_pk_fma_f32 v[62:63], v[40:41], v[48:49], v[16:17] op_sel_hi:[0,1,1]
	v_pk_fma_f32 v[20:21], v[92:93], v[20:21], v[46:47]
	v_pk_fma_f32 v[10:11], v[60:61], v[10:11], v[18:19]
	v_pk_mul_f32 v[18:19], v[64:65], v[62:63]
	v_pk_mul_f32 v[24:25], v[24:25], v[62:63]
	v_pk_fma_f32 v[58:59], v[40:41], v[52:53], v[20:21] op_sel_hi:[0,1,1]
	v_pk_fma_f32 v[18:19], v[60:61], v[66:67], v[18:19]
	v_pk_fma_f32 v[24:25], v[60:61], v[26:27], v[24:25]
	v_pk_fma_f32 v[18:19], v[58:59], v[84:85], v[18:19]
	v_pk_fma_f32 v[24:25], v[58:59], v[28:29], v[24:25]
	v_pk_mul_f32 v[16:17], v[68:69], v[22:23] op_sel_hi:[1,0]
	v_pk_fma_f32 v[18:19], v[56:57], v[86:87], v[18:19]
	v_pk_fma_f32 v[24:25], v[56:57], v[30:31], v[24:25]
	v_pk_fma_f32 v[8:9], v[62:63], v[8:9], v[16:17]
	v_add_f32_e32 v16, v18, v19
	v_add_f32_e32 v24, v25, v24
	s_waitcnt lgkmcnt(2)
	v_pk_mul_f32 v[54:55], v[74:75], v[22:23] op_sel_hi:[1,0]
	v_add_f32_dpp v16, v16, v16 quad_perm:[1,0,3,2] row_mask:0xf bank_mask:0xf bound_ctrl:1
	v_add_f32_dpp v24, v24, v24 quad_perm:[1,0,3,2] row_mask:0xf bank_mask:0xf bound_ctrl:1
	v_pk_mul_f32 v[20:21], v[72:73], v[22:23] op_sel_hi:[1,0]
	v_add_f32_dpp v16, v16, v16 quad_perm:[2,3,0,1] row_mask:0xf bank_mask:0xf bound_ctrl:1
	v_add_f32_dpp v24, v24, v24 quad_perm:[2,3,0,1] row_mask:0xf bank_mask:0xf bound_ctrl:1
	v_pk_fma_f32 v[14:15], v[56:57], v[14:15], v[54:55]
	v_add_f32_dpp v16, v16, v16 row_half_mirror row_mask:0xf bank_mask:0xf bound_ctrl:1
	v_add_f32_dpp v24, v24, v24 row_half_mirror row_mask:0xf bank_mask:0xf bound_ctrl:1
	ds_write_b32 v151, v16 offset:2688
	v_pk_fma_f32 v[26:27], v[24:25], v[32:33], v[8:9] op_sel_hi:[0,1,1]
	v_pk_fma_f32 v[12:13], v[58:59], v[12:13], v[20:21]
	ds_read_b128 v[16:19], v149 offset:29440
	ds_read_b128 v[20:23], v149 offset:29456
	ds_read_b128 v[40:43], v149 offset:29696
	ds_read_b128 v[44:47], v149 offset:29712
	ds_read_b128 v[48:51], v149 offset:29952
	ds_read_b128 v[52:55], v149 offset:29968
	ds_read_b128 v[88:91], v149 offset:30208
	ds_read_b128 v[92:95], v149 offset:30224
	ds_read_b128 v[108:111], v149 offset:30464
	ds_read_b128 v[112:115], v149 offset:30480
	ds_read_b32 v106, v150 offset:2944
	v_pk_fma_f32 v[28:29], v[24:25], v[34:35], v[10:11] op_sel_hi:[0,1,1]
	s_waitcnt lgkmcnt(8)
; DI float red8(float x) { x += dppf(x, 0); x += dppf(x, 1); x += dppf(x, 2); return x; }
; DI void scan_item(const Params& p, int L, int c, int item, char* smem, bool dry) {
;     ...
;   auto load_raw = [&](int tc) {
;     const int lr = b * 4096 + tc * 32 + tt;
;     const int s = c * 4096 + tc * 32 + tt;
;     const u16* cur = U + (size_t)lr * LDU_R;
;     const u16* prv = (s == 0) ? (BND + (size_t)4 * SHIFTW) : ((s == 4096 && c == 1) ? (BND + (size_t)b * SHIFTW) : (cur - LDU_R));
;     ...
;   auto steps8 = [&](const float* PA, const float* Vst, float* Yst, int t0) {
; #pragma unroll
;     for (int t8 = 0; t8 < 8; ++t8) {
;       const int t = t0 + t8;
;       const float* pa = PA + (t + 1) * 320 + ks * 8;
;       const float4 xd0 = *(const float4*)(pa), xd1 = *(const float4*)(pa + 4);
;       const float4 xn0 = *(const float4*)(pa + 64), xn1 = *(const float4*)(pa + 68);
;       const float4 xb0 = *(const float4*)(pa + 128), xb1 = *(const float4*)(pa + 132);
;       const float4 xk0 = *(const float4*)(pa + 192), xk1 = *(const float4*)(pa + 196);
;       const float4 xr0 = *(const float4*)(pa + 256), xr1 = *(const float4*)(pa + 260);
;       const float xvv = Vst[(t + 1) * 32 + row32];
;       float sa0 = S[0] * n0.x, sa1 = S[1] * n0.y;
;       sa0 = fmaf(S[2], n0.z, sa0); sa1 = fmaf(S[3], n0.w, sa1);
;       sa0 = fmaf(S[4], n1.x, sa0); sa1 = fmaf(S[5], n1.y, sa1);
;       sa0 = fmaf(S[6], n1.z, sa0); sa1 = fmaf(S[7], n1.w, sa1);
;       float sa = red8(sa0 + sa1);
;       S[0] = fmaf(sa, b0.x, fmaf(S[0], d0.x, vv * k0.x)); S[1] = fmaf(sa, b0.y, fmaf(S[1], d0.y, vv * k0.y));
;       S[2] = fmaf(sa, b0.z, fmaf(S[2], d0.z, vv * k0.z)); S[3] = fmaf(sa, b0.w, fmaf(S[3], d0.w, vv * k0.w));
;       S[4] = fmaf(sa, b1.x, fmaf(S[4], d1.x, vv * k1.x)); S[5] = fmaf(sa, b1.y, fmaf(S[5], d1.y, vv * k1.y));
;       S[6] = fmaf(sa, b1.z, fmaf(S[6], d1.z, vv * k1.z)); S[7] = fmaf(sa, b1.w, fmaf(S[7], d1.w, vv * k1.w));
;       float y0 = S[0] * r0.x, y1 = S[1] * r0.y;
;       y0 = fmaf(S[2], r0.z, y0); y1 = fmaf(S[3], r0.w, y1);
;       y0 = fmaf(S[4], r1.x, y0); y1 = fmaf(S[5], r1.y, y1);
;       y0 = fmaf(S[6], r1.z, y0); y1 = fmaf(S[7], r1.w, y1);
;       float y = red8(y0 + y1);
;       Yst[t * 32 + row32] = y;
;       d0 = xd0; d1 = xd1; n0 = xn0; n1 = xn1; b0 = xb0; b1 = xb1; k0 = xk0; k1 = xk1; r0 = xr0; r1 = xr1; vv = xvv;
;     }
	v_pk_mul_f32 v[32:33], v[40:41], v[26:27]
	v_pk_fma_f32 v[30:31], v[24:25], v[36:37], v[12:13] op_sel_hi:[0,1,1]
	v_pk_fma_f32 v[32:33], v[28:29], v[42:43], v[32:33]
	v_pk_fma_f32 v[24:25], v[24:25], v[38:39], v[14:15] op_sel_hi:[0,1,1]
	v_pk_mul_f32 v[8:9], v[76:77], v[26:27]
	s_waitcnt lgkmcnt(7)
	v_pk_fma_f32 v[32:33], v[30:31], v[44:45], v[32:33]
	v_pk_fma_f32 v[8:9], v[28:29], v[78:79], v[8:9]
	v_pk_fma_f32 v[32:33], v[24:25], v[46:47], v[32:33]
	v_pk_fma_f32 v[8:9], v[30:31], v[80:81], v[8:9]
	v_add_f32_e32 v32, v33, v32
	v_pk_fma_f32 v[8:9], v[24:25], v[82:83], v[8:9]
	s_nop 0
	v_add_f32_dpp v32, v32, v32 quad_perm:[1,0,3,2] row_mask:0xf bank_mask:0xf bound_ctrl:1
	v_add_f32_e32 v8, v8, v9
	s_waitcnt lgkmcnt(0)
	v_pk_mul_f32 v[34:35], v[88:89], v[106:107] op_sel_hi:[1,0]
	v_add_f32_dpp v32, v32, v32 quad_perm:[2,3,0,1] row_mask:0xf bank_mask:0xf bound_ctrl:1
	v_add_f32_dpp v8, v8, v8 quad_perm:[1,0,3,2] row_mask:0xf bank_mask:0xf bound_ctrl:1
	v_pk_fma_f32 v[16:17], v[26:27], v[16:17], v[34:35]
	v_add_f32_dpp v32, v32, v32 row_half_mirror row_mask:0xf bank_mask:0xf bound_ctrl:1
	v_add_f32_dpp v8, v8, v8 quad_perm:[2,3,0,1] row_mask:0xf bank_mask:0xf bound_ctrl:1
	v_pk_fma_f32 v[88:89], v[32:33], v[48:49], v[16:17] op_sel_hi:[0,1,1]
	v_pk_mul_f32 v[16:17], v[90:91], v[106:107] op_sel_hi:[1,0]
	v_add_f32_dpp v8, v8, v8 row_half_mirror row_mask:0xf bank_mask:0xf bound_ctrl:1
	v_pk_fma_f32 v[16:17], v[28:29], v[18:19], v[16:17]
	ds_write_b32 v151, v8 offset:2816
	v_pk_fma_f32 v[90:91], v[32:33], v[50:51], v[16:17] op_sel_hi:[0,1,1]
	v_pk_mul_f32 v[16:17], v[92:93], v[106:107] op_sel_hi:[1,0]
	ds_read_b128 v[56:59], v149 offset:30720
	ds_read_b128 v[68:71], v149 offset:30736
	ds_read_b128 v[84:87], v149 offset:30976
	ds_read_b128 v[80:83], v149 offset:30992
	ds_read_b128 v[60:63], v149 offset:31232
	ds_read_b128 v[72:75], v149 offset:31248
	ds_read_b128 v[64:67], v149 offset:31488
	ds_read_b128 v[76:79], v149 offset:31504
	ds_read_b128 v[12:15], v149 offset:31744
	ds_read_b128 v[8:11], v149 offset:31760
	v_pk_fma_f32 v[16:17], v[30:31], v[20:21], v[16:17]
	s_nop 0
	v_pk_fma_f32 v[92:93], v[32:33], v[52:53], v[16:17] op_sel_hi:[0,1,1]
	v_pk_mul_f32 v[16:17], v[94:95], v[106:107] op_sel_hi:[1,0]
	ds_read_b32 v94, v150 offset:3072
	v_pk_fma_f32 v[16:17], v[24:25], v[22:23], v[16:17]
	s_nop 0
	v_pk_fma_f32 v[106:107], v[32:33], v[54:55], v[16:17] op_sel_hi:[0,1,1]
	v_pk_mul_f32 v[16:17], v[108:109], v[88:89]
	v_pk_fma_f32 v[16:17], v[90:91], v[110:111], v[16:17]
	v_pk_fma_f32 v[16:17], v[92:93], v[112:113], v[16:17]
	v_pk_fma_f32 v[16:17], v[106:107], v[114:115], v[16:17]
	v_add_f32_e32 v16, v16, v17
	s_nop 1
	v_add_f32_dpp v16, v16, v16 quad_perm:[1,0,3,2] row_mask:0xf bank_mask:0xf bound_ctrl:1
	s_nop 1
	v_add_f32_dpp v16, v16, v16 quad_perm:[2,3,0,1] row_mask:0xf bank_mask:0xf bound_ctrl:1
	s_nop 1
	v_add_f32_dpp v16, v16, v16 row_half_mirror row_mask:0xf bank_mask:0xf bound_ctrl:1
	ds_write_b32 v151, v16 offset:2944
	v_add_u32_e32 v16, s29, v99
	v_cmp_lt_i32_e32 vcc, s69, v16
	s_and_saveexec_b64 s[22:23], vcc
	s_xor_b64 s[22:23], exec, s[22:23]
	s_cbranch_execz .LBB0_160
	v_cmp_eq_u32_e32 vcc, s73, v16
	s_mov_b64 s[18:19], -1
	s_and_saveexec_b64 s[24:25], vcc
	s_cbranch_execz .LBB0_159
	v_readlane_b32 s18, v254, 23
	v_readlane_b32 s19, v254, 24
	s_orn2_b64 s[18:19], s[18:19], exec

; DI void grid_barrier(unsigned* bar, unsigned& epoch) {
;   __syncthreads();
;   ++epoch;
;   if (threadIdx.x == 0) {
;     __builtin_amdgcn_fence(__ATOMIC_RELEASE, "agent");
;     asm volatile("s_waitcnt vmcnt(0)" ::: "memory");
;     const unsigned target = epoch * gridDim.x;
;     __hip_atomic_fetch_add(bar, 1u, __ATOMIC_RELAXED, __HIP_MEMORY_SCOPE_AGENT);
;     unsigned spins = 0;
;     while (__hip_atomic_load(bar, __ATOMIC_RELAXED, __HIP_MEMORY_SCOPE_AGENT) < target) {
;       if (spins < 64u) __builtin_amdgcn_s_sleep(2); else __builtin_amdgcn_s_sleep(16);
;       if (++spins > (1u << 22)) break;
;     }
;     __builtin_amdgcn_fence(__ATOMIC_ACQUIRE, "agent");
;     asm volatile("s_waitcnt vmcnt(0)" ::: "memory");
;   }
;   __syncthreads();
; }
.Lmy_xb_have:
	s_nop 1
	v_readlane_b32 s8, v255, 40
	v_readlane_b32 s98, v255, 41
	v_mov_b32_e32 v0, 1
	global_atomic_add v0, v199, v0, s[6:7] offset:-2304 sc0
	s_waitcnt vmcnt(0)
	s_nop 0
	v_readfirstlane_b32 s99, v0
	s_add_i32 s99, s99, 1
	s_mul_i32 s8, s8, s9
	s_cmp_eq_u32 s99, s8
	s_cbranch_scc0 .Lmy_xb_wait_local
	buffer_wbl2 sc1
	s_waitcnt vmcnt(0)
	v_mov_b32_e32 v0, 1
	global_atomic_add v0, v199, v0, s[10:11] offset:-256 sc0
	s_waitcnt vmcnt(0)
	s_nop 0
	v_readfirstlane_b32 s99, v0
	s_add_i32 s99, s99, 1
	s_mul_i32 s8, s98, s9
	s_cmp_eq_u32 s99, s8
	s_cbranch_scc0 .Lmy_xb_wait_local
	v_mov_b32_e32 v0, 1
	global_atomic_add v199, v0, s[10:11] offset:-1280
	global_atomic_add v199, v0, s[10:11] offset:-1152
	global_atomic_add v199, v0, s[10:11] offset:-1024
	global_atomic_add v199, v0, s[10:11] offset:-896
	global_atomic_add v199, v0, s[10:11] offset:-768
	global_atomic_add v199, v0, s[10:11] offset:-640
	global_atomic_add v199, v0, s[10:11] offset:-512
	global_atomic_add v199, v0, s[10:11] offset:-384
	s_branch .Lmy_to_67
